# seam_rows loops: loop-invariant gain vector loads hoisted out of the row loops (4 instances), their per-pair vmcnt waits replaced by s_nop 0
# baseline (speedup 1.0000x reference)
; __device__ __forceinline__ u32x4 pack8(const float* f) { u32x4 w; w.x = pk2(f[0], f[1]); w.y = pk2(f[2], f[3]); w.z = pk2(f[4], f[5]); w.w = pk2(f[6], f[7]); return w; }
; template <bool HAS_M, bool WRITE_X, bool WRITE_HN>
; __device__ __forceinline__ void seam_rows(const float* xin, const bf16_t* mb, const float* gpost, const float* gpre, float* xout, bf16_t* hn, int gw, int NGW, int lane) {
;     for (int row = gw; row < M; row += NGW) {
;         const size_t ro = (size_t)row * DM + lane * 8;
;         float v[32];
; #pragma unroll
;         for (int s = 0; s < 4; ++s) ld8f(xin + ro + s * 512, v + s * 8);
;         if (HAS_M) {
;             float mv[32]; float ss = 0.f;
; #pragma unroll
;             for (int s = 0; s < 4; ++s) unpack8(*(const u32x4*)(mb + ro + s * 512), mv + s * 8);
; #pragma unroll
;             for (int i = 0; i < 32; ++i) ss += mv[i] * mv[i];
;             const float r1 = rsqrtf(wave_sum(ss) * (1.f / 2048.f) + 1e-6f);
; #pragma unroll
;             for (int s = 0; s < 4; ++s) { float g[8]; ld8f(gpost + s * 512 + lane * 8, g);
; #pragma unroll
;                 for (int i = 0; i < 8; ++i) v[s * 8 + i] += mv[s * 8 + i] * r1 * g[i]; }
;         }
;         if (WRITE_X) {
; #pragma unroll
;             for (int s = 0; s < 4; ++s) { *(f32x4*)(xout + ro + s * 512) = (f32x4){v[s * 8], v[s * 8 + 1], v[s * 8 + 2], v[s * 8 + 3]}; *(f32x4*)(xout + ro + s * 512 + 4) = (f32x4){v[s * 8 + 4], v[s * 8 + 5], v[s * 8 + 6], v[s * 8 + 7]}; }
;         }
;         if (WRITE_HN) {
;             float ss = 0.f;
; #pragma unroll
;             for (int i = 0; i < 32; ++i) ss += v[i] * v[i];
;             const float r2 = rsqrtf(wave_sum(ss) * (1.f / 2048.f) + 1e-6f);
; #pragma unroll
;             for (int s = 0; s < 4; ++s) { float g[8], o[8]; ld8f(gpre + s * 512 + lane * 8, g);
; #pragma unroll
;                 for (int i = 0; i < 8; ++i) o[i] = v[s * 8 + i] * r2 * g[i];
;                 *(u32x4*)(hn + ro + s * 512) = pack8(o); }
.LBB0_78:
	s_cmpk_gt_i32 s10, 0x3fff
	s_cbranch_scc1 .LBB0_81
	v_cmp_lt_i32_e32 vcc, v213, v212
	s_load_dwordx2 s[18:19], s[64:65], 0xf8
	s_load_dwordx4 s[28:31], s[64:65], 0x10
	s_waitcnt vmcnt(0)
	v_cndmask_b32_e32 v0, v211, v213, vcc
	v_cmp_lt_i32_e32 vcc, v210, v212
	v_lshlrev_b32_e32 v28, 2, v0
	v_lshlrev_b32_e32 v128, 5, v40
	v_cndmask_b32_e32 v0, v211, v210, vcc
	v_lshlrev_b32_e32 v29, 2, v0
	v_xor_b32_e32 v0, 4, v211
	v_cmp_lt_i32_e32 vcc, v0, v212
	s_ashr_i32 s2, s26, 31
	s_ashr_i32 s7, s17, 31
	v_cndmask_b32_e32 v0, v211, v0, vcc
	v_lshlrev_b32_e32 v30, 2, v0
	v_xor_b32_e32 v0, 8, v211
	v_cmp_lt_i32_e32 vcc, v0, v212
	s_waitcnt lgkmcnt(0)
	v_lshl_add_u64 v[2:3], s[30:31], 0, v[128:129]
	s_add_u32 s26, s26, s17
	v_cndmask_b32_e32 v0, v211, v0, vcc
	v_lshlrev_b32_e32 v31, 2, v0
	v_xor_b32_e32 v0, 16, v211
	v_cmp_lt_i32_e32 vcc, v0, v212
	s_addc_u32 s27, s2, s7
	s_mov_b64 s[30:31], 0x3800
	v_cndmask_b32_e32 v0, v211, v0, vcc
	v_cmp_lt_i32_e32 vcc, v218, v212
	v_lshlrev_b32_e32 v32, 2, v0
	v_lshl_add_u64 v[22:23], v[2:3], 0, s[30:31]
	v_cndmask_b32_e32 v0, v211, v218, vcc
	v_lshlrev_b32_e32 v33, 2, v0
	v_lshl_add_u64 v[0:1], s[28:29], 0, v[128:129]
	s_mov_b64 s[28:29], 0x2000
	v_lshl_add_u64 v[12:13], v[0:1], 0, s[28:29]
	v_lshl_add_u64 v[14:15], v[2:3], 0, s[28:29]
	s_mov_b64 s[28:29], 0x3000
	v_lshl_add_u64 v[16:17], v[0:1], 0, s[28:29]
	v_lshl_add_u64 v[20:21], v[2:3], 0, s[28:29]
	s_lshl_b64 s[28:29], s[26:27], 13
	s_add_u32 s18, s18, s28
	s_addc_u32 s19, s19, s29
	s_ashr_i32 s17, s16, 31
	v_lshl_add_u64 v[18:19], v[0:1], 0, s[30:31]
	v_lshl_add_u64 v[0:1], s[18:19], 0, v[128:129]
	s_lshl_b64 s[18:19], s[16:17], 13
	s_lshl_b64 s[26:27], s[26:27], 12
	s_add_u32 s26, s83, s26
	v_lshlrev_b32_e32 v128, 4, v40
	s_addc_u32 s27, s93, s27
	v_lshl_add_u64 v[24:25], v[0:1], 0, s[44:45]
	v_lshl_add_u64 v[26:27], s[26:27], 0, v[128:129]
	s_lshl_b64 s[30:31], s[16:17], 12
	global_load_dwordx4 v[152:155], v[14:15], off offset:16
	global_load_dwordx4 v[156:159], v[14:15], off
	global_load_dwordx4 v[160:163], v[14:15], off offset:2048
	global_load_dwordx4 v[164:167], v[14:15], off offset:2064
	global_load_dwordx4 v[168:171], v[20:21], off
	global_load_dwordx4 v[172:175], v[20:21], off offset:16
	global_load_dwordx4 v[176:179], v[22:23], off
	global_load_dwordx4 v[180:183], v[22:23], off offset:16
.LBB0_80:
	v_add_co_u32_e32 v0, vcc, 0xec000000, v26
	s_add_i32 s10, s10, s16
	s_nop 0
	v_addc_co_u32_e32 v1, vcc, -1, v27, vcc
	global_load_dwordx4 v[8:11], v[0:1], off
	v_add_co_u32_e32 v0, vcc, 0xec001000, v26
	s_cmpk_gt_i32 s10, 0x3fff
	s_nop 0
	v_addc_co_u32_e32 v1, vcc, -1, v27, vcc
	global_load_dwordx4 v[34:37], v[0:1], off offset:-3072
	global_load_dwordx4 v[38:41], v[0:1], off offset:-2048
	global_load_dwordx4 v[42:45], v[0:1], off offset:-1024
	global_load_dwordx4 v[46:49], v[24:25], off offset:-4080
	global_load_dwordx4 v[50:53], v[24:25], off offset:-4096
	global_load_dwordx4 v[54:57], v[24:25], off offset:-2032
	global_load_dwordx4 v[58:61], v[24:25], off offset:-2048
	global_load_dwordx4 v[4:7], v[24:25], off offset:16
	global_load_dwordx4 v[62:65], v[24:25], off
	global_load_dwordx4 v[0:3], v[24:25], off offset:2064
	global_load_dwordx4 v[66:69], v[24:25], off offset:2048
	global_load_dwordx4 v[70:73], v[12:13], off offset:16
	global_load_dwordx4 v[74:77], v[12:13], off
	global_load_dwordx4 v[78:81], v[12:13], off offset:2064
	global_load_dwordx4 v[82:85], v[12:13], off offset:2048
	global_load_dwordx4 v[86:89], v[16:17], off offset:16
	global_load_dwordx4 v[90:93], v[16:17], off
	global_load_dwordx4 v[94:97], v[18:19], off offset:16
	global_load_dwordx4 v[98:101], v[18:19], off
	s_waitcnt vmcnt(18)
	v_lshlrev_b32_e32 v114, 16, v34
	v_and_b32_e32 v115, 0xffff0000, v34
	v_pk_mul_f32 v[126:127], v[114:115], v[114:115]
	v_lshlrev_b32_e32 v34, 16, v35
	v_and_b32_e32 v35, 0xffff0000, v35
	v_pk_mul_f32 v[130:131], v[34:35], v[34:35]
	v_lshlrev_b32_e32 v116, 16, v36
	v_and_b32_e32 v117, 0xffff0000, v36
	v_pk_mul_f32 v[132:133], v[116:117], v[116:117]
	v_lshlrev_b32_e32 v36, 16, v37
	v_and_b32_e32 v37, 0xffff0000, v37
	v_pk_mul_f32 v[134:135], v[36:37], v[36:37]
	v_lshlrev_b32_e32 v102, 16, v8
	v_and_b32_e32 v103, 0xffff0000, v8
	v_lshlrev_b32_e32 v8, 16, v9
	v_and_b32_e32 v9, 0xffff0000, v9
	v_pk_mul_f32 v[106:107], v[102:103], v[102:103]
	v_pk_mul_f32 v[108:109], v[8:9], v[8:9]
	v_add_f32_e32 v106, v106, v107
	v_lshlrev_b32_e32 v104, 16, v10
	v_and_b32_e32 v105, 0xffff0000, v10
	v_add_f32_e32 v106, v108, v106
	v_pk_mul_f32 v[110:111], v[104:105], v[104:105]
	v_add_f32_e32 v106, v109, v106
	v_lshlrev_b32_e32 v10, 16, v11
	v_and_b32_e32 v11, 0xffff0000, v11
	v_add_f32_e32 v106, v110, v106
	v_pk_mul_f32 v[112:113], v[10:11], v[10:11]
	v_add_f32_e32 v106, v111, v106
	v_add_f32_e32 v106, v112, v106
	v_add_f32_e32 v106, v113, v106
	v_add_f32_e32 v106, v126, v106
	v_add_f32_e32 v106, v127, v106
	v_add_f32_e32 v106, v130, v106
	v_add_f32_e32 v106, v131, v106
	v_add_f32_e32 v106, v132, v106
	v_add_f32_e32 v106, v133, v106
	s_waitcnt vmcnt(17)
	v_lshlrev_b32_e32 v118, 16, v38
	v_and_b32_e32 v119, 0xffff0000, v38
	v_add_f32_e32 v106, v134, v106
	v_pk_mul_f32 v[136:137], v[118:119], v[118:119]
	v_add_f32_e32 v106, v135, v106
	v_lshlrev_b32_e32 v38, 16, v39
	v_and_b32_e32 v39, 0xffff0000, v39
	v_add_f32_e32 v106, v136, v106
	v_pk_mul_f32 v[138:139], v[38:39], v[38:39]
	v_add_f32_e32 v106, v137, v106
	v_lshlrev_b32_e32 v120, 16, v40
	v_and_b32_e32 v121, 0xffff0000, v40
	v_add_f32_e32 v106, v138, v106
	v_pk_mul_f32 v[140:141], v[120:121], v[120:121]
	v_add_f32_e32 v106, v139, v106
	v_lshlrev_b32_e32 v40, 16, v41
	v_and_b32_e32 v41, 0xffff0000, v41
	v_add_f32_e32 v106, v140, v106
	v_pk_mul_f32 v[142:143], v[40:41], v[40:41]
	v_add_f32_e32 v106, v141, v106
	s_waitcnt vmcnt(16)
; template <bool HAS_M, bool WRITE_X, bool WRITE_HN>
; __device__ __forceinline__ void seam_rows(const float* xin, const bf16_t* mb, const float* gpost, const float* gpre, float* xout, bf16_t* hn, int gw, int NGW, int lane) {
;     ...
;         if (HAS_M) {
;             float mv[32]; float ss = 0.f;
; #pragma unroll
;             for (int s = 0; s < 4; ++s) unpack8(*(const u32x4*)(mb + ro + s * 512), mv + s * 8);
; #pragma unroll
;             for (int i = 0; i < 32; ++i) ss += mv[i] * mv[i];
;             const float r1 = rsqrtf(wave_sum(ss) * (1.f / 2048.f) + 1e-6f);
; #pragma unroll
;             for (int s = 0; s < 4; ++s) { float g[8]; ld8f(gpost + s * 512 + lane * 8, g);
; #pragma unroll
;                 for (int i = 0; i < 8; ++i) v[s * 8 + i] += mv[s * 8 + i] * r1 * g[i]; }
;         }
;         if (WRITE_X) {
; #pragma unroll
;             for (int s = 0; s < 4; ++s) { *(f32x4*)(xout + ro + s * 512) = (f32x4){v[s * 8], v[s * 8 + 1], v[s * 8 + 2], v[s * 8 + 3]}; *(f32x4*)(xout + ro + s * 512 + 4) = (f32x4){v[s * 8 + 4], v[s * 8 + 5], v[s * 8 + 6], v[s * 8 + 7]}; }
;         }
;         if (WRITE_HN) {
;             float ss = 0.f;
; #pragma unroll
;             for (int i = 0; i < 32; ++i) ss += v[i] * v[i];
;             const float r2 = rsqrtf(wave_sum(ss) * (1.f / 2048.f) + 1e-6f);
	v_lshlrev_b32_e32 v122, 16, v42
	v_and_b32_e32 v123, 0xffff0000, v42
	v_add_f32_e32 v106, v142, v106
	v_pk_mul_f32 v[144:145], v[122:123], v[122:123]
	v_add_f32_e32 v106, v143, v106
	v_lshlrev_b32_e32 v42, 16, v43
	v_and_b32_e32 v43, 0xffff0000, v43
	v_add_f32_e32 v106, v144, v106
	v_pk_mul_f32 v[146:147], v[42:43], v[42:43]
	v_add_f32_e32 v106, v145, v106
	v_lshlrev_b32_e32 v124, 16, v44
	v_and_b32_e32 v125, 0xffff0000, v44
	v_add_f32_e32 v106, v146, v106
	v_pk_mul_f32 v[148:149], v[124:125], v[124:125]
	v_add_f32_e32 v106, v147, v106
	v_lshlrev_b32_e32 v44, 16, v45
	v_and_b32_e32 v45, 0xffff0000, v45
	v_add_f32_e32 v106, v148, v106
	v_pk_mul_f32 v[150:151], v[44:45], v[44:45]
	v_add_f32_e32 v106, v149, v106
	v_add_f32_e32 v106, v150, v106
	v_add_f32_e32 v106, v151, v106
	ds_bpermute_b32 v107, v28, v106
	s_waitcnt lgkmcnt(0)
	v_add_f32_e32 v106, v106, v107
	ds_bpermute_b32 v107, v29, v106
	s_waitcnt lgkmcnt(0)
	v_add_f32_e32 v106, v106, v107
	ds_bpermute_b32 v107, v30, v106
	s_waitcnt lgkmcnt(0)
	v_add_f32_e32 v106, v106, v107
	ds_bpermute_b32 v107, v31, v106
	s_waitcnt lgkmcnt(0)
	v_add_f32_e32 v106, v106, v107
	ds_bpermute_b32 v107, v32, v106
	s_waitcnt lgkmcnt(0)
	v_add_f32_e32 v106, v106, v107
	ds_bpermute_b32 v107, v33, v106
	s_waitcnt lgkmcnt(0)
	v_add_f32_e32 v106, v106, v107
	v_fmamk_f32 v106, v106, 0x3a000000, v209
	v_mul_f32_e32 v107, 0x4b800000, v106
	v_cmp_gt_f32_e32 vcc, s15, v106
	s_nop 1
	v_cndmask_b32_e32 v106, v106, v107, vcc
	v_rsq_f32_e32 v106, v106
	s_nop 0
	v_mul_f32_e32 v107, 0x45800000, v106
	v_cndmask_b32_e32 v106, v106, v107, vcc
	v_pk_mul_f32 v[102:103], v[106:107], v[102:103] op_sel_hi:[0,1]
	v_pk_mul_f32 v[8:9], v[106:107], v[8:9] op_sel_hi:[0,1]
	v_pk_mul_f32 v[104:105], v[106:107], v[104:105] op_sel_hi:[0,1]
	v_pk_mul_f32 v[110:111], v[106:107], v[34:35] op_sel_hi:[0,1]
	v_pk_mul_f32 v[112:113], v[106:107], v[116:117] op_sel_hi:[0,1]
	s_waitcnt vmcnt(6)
	v_pk_fma_f32 v[34:35], v[74:75], v[102:103], v[50:51]
	v_pk_mul_f32 v[10:11], v[106:107], v[10:11] op_sel_hi:[0,1]
	v_pk_mul_f32 v[108:109], v[106:107], v[114:115] op_sel_hi:[0,1]
	v_pk_mul_f32 v[114:115], v[106:107], v[36:37] op_sel_hi:[0,1]
	v_pk_mul_f32 v[116:117], v[106:107], v[118:119] op_sel_hi:[0,1]
	v_pk_mul_f32 v[118:119], v[106:107], v[38:39] op_sel_hi:[0,1]
	v_pk_mul_f32 v[120:121], v[106:107], v[120:121] op_sel_hi:[0,1]
	v_pk_mul_f32 v[126:127], v[106:107], v[40:41] op_sel_hi:[0,1]
	v_pk_mul_f32 v[122:123], v[106:107], v[122:123] op_sel_hi:[0,1]
	v_pk_mul_f32 v[130:131], v[106:107], v[42:43] op_sel_hi:[0,1]
	v_pk_mul_f32 v[124:125], v[106:107], v[124:125] op_sel_hi:[0,1]
	v_pk_mul_f32 v[106:107], v[106:107], v[44:45] op_sel_hi:[0,1]
	v_pk_fma_f32 v[36:37], v[76:77], v[8:9], v[52:53]
	v_pk_fma_f32 v[38:39], v[70:71], v[104:105], v[46:47]
	s_waitcnt vmcnt(5)
	v_pk_fma_f32 v[46:47], v[78:79], v[112:113], v[54:55]
	v_pk_mul_f32 v[54:55], v[34:35], v[34:35]
	v_pk_fma_f32 v[40:41], v[72:73], v[10:11], v[48:49]
	s_waitcnt vmcnt(4)
	v_pk_fma_f32 v[42:43], v[82:83], v[108:109], v[58:59]
	v_pk_fma_f32 v[44:45], v[84:85], v[110:111], v[60:61]
	v_pk_fma_f32 v[48:49], v[80:81], v[114:115], v[56:57]
	s_waitcnt vmcnt(2)
	v_pk_fma_f32 v[50:51], v[90:91], v[116:117], v[62:63]
	v_pk_fma_f32 v[52:53], v[92:93], v[118:119], v[64:65]
	v_pk_fma_f32 v[8:9], v[86:87], v[120:121], v[4:5]
	v_pk_fma_f32 v[10:11], v[88:89], v[126:127], v[6:7]
	s_waitcnt vmcnt(0)
	v_pk_fma_f32 v[4:5], v[98:99], v[122:123], v[66:67]
	v_pk_fma_f32 v[6:7], v[100:101], v[130:131], v[68:69]
	v_pk_fma_f32 v[0:1], v[94:95], v[124:125], v[0:1]
	v_pk_fma_f32 v[2:3], v[96:97], v[106:107], v[2:3]
	global_store_dwordx4 v[24:25], v[34:37], off offset:-4096
	global_store_dwordx4 v[24:25], v[38:41], off offset:-4080
	global_store_dwordx4 v[24:25], v[42:45], off offset:-2048
	global_store_dwordx4 v[24:25], v[46:49], off offset:-2032
	global_store_dwordx4 v[24:25], v[50:53], off
	global_store_dwordx4 v[24:25], v[8:11], off offset:16
	global_store_dwordx4 v[24:25], v[4:7], off offset:2048
	global_store_dwordx4 v[24:25], v[0:3], off offset:2064
	v_pk_mul_f32 v[62:63], v[36:37], v[36:37]
	v_add_f32_e32 v54, v54, v55
	v_add_f32_e32 v62, v62, v54
	v_pk_mul_f32 v[64:65], v[38:39], v[38:39]
	v_add_f32_e32 v62, v63, v62
	v_add_f32_e32 v62, v64, v62
	v_pk_mul_f32 v[66:67], v[40:41], v[40:41]
	v_add_f32_e32 v62, v65, v62
	v_add_f32_e32 v62, v66, v62
	v_pk_mul_f32 v[68:69], v[42:43], v[42:43]
	v_add_f32_e32 v62, v67, v62
	v_add_f32_e32 v62, v68, v62
	v_pk_mul_f32 v[70:71], v[44:45], v[44:45]
	v_add_f32_e32 v62, v69, v62
	v_add_f32_e32 v62, v70, v62
	v_pk_mul_f32 v[72:73], v[46:47], v[46:47]
	v_add_f32_e32 v62, v71, v62
	v_add_f32_e32 v62, v72, v62
	v_pk_mul_f32 v[74:75], v[48:49], v[48:49]
	v_add_f32_e32 v62, v73, v62
	v_add_f32_e32 v62, v74, v62
	v_pk_mul_f32 v[76:77], v[50:51], v[50:51]
	v_add_f32_e32 v62, v75, v62
	v_add_f32_e32 v62, v76, v62
	v_pk_mul_f32 v[78:79], v[52:53], v[52:53]
	v_add_f32_e32 v62, v77, v62
	v_add_f32_e32 v62, v78, v62
	v_pk_mul_f32 v[80:81], v[8:9], v[8:9]
	v_add_f32_e32 v62, v79, v62
	v_add_f32_e32 v62, v80, v62
	v_pk_mul_f32 v[82:83], v[10:11], v[10:11]
	v_add_f32_e32 v62, v81, v62
	v_add_f32_e32 v62, v82, v62
	v_pk_mul_f32 v[84:85], v[4:5], v[4:5]
	v_add_f32_e32 v62, v83, v62
	v_add_f32_e32 v62, v84, v62
	v_pk_mul_f32 v[86:87], v[6:7], v[6:7]
	v_add_f32_e32 v62, v85, v62
	v_add_f32_e32 v62, v86, v62
	v_pk_mul_f32 v[88:89], v[0:1], v[0:1]
	v_add_f32_e32 v62, v87, v62
	v_add_f32_e32 v62, v88, v62
	v_pk_mul_f32 v[90:91], v[2:3], v[2:3]
	v_add_f32_e32 v62, v89, v62
	v_add_f32_e32 v62, v90, v62
	v_add_f32_e32 v62, v91, v62
	ds_bpermute_b32 v63, v28, v62
	v_lshl_add_u64 v[24:25], v[24:25], 0, s[18:19]
	s_waitcnt lgkmcnt(0)
; __device__ __forceinline__ u32x4 pack8(const float* f) { u32x4 w; w.x = pk2(f[0], f[1]); w.y = pk2(f[2], f[3]); w.z = pk2(f[4], f[5]); w.w = pk2(f[6], f[7]); return w; }
; template <bool HAS_M, bool WRITE_X, bool WRITE_HN>
; __device__ __forceinline__ void seam_rows(const float* xin, const bf16_t* mb, const float* gpost, const float* gpre, float* xout, bf16_t* hn, int gw, int NGW, int lane) {
;     ...
;         if (WRITE_HN) {
;             float ss = 0.f;
; #pragma unroll
;             for (int i = 0; i < 32; ++i) ss += v[i] * v[i];
;             const float r2 = rsqrtf(wave_sum(ss) * (1.f / 2048.f) + 1e-6f);
; #pragma unroll
;             for (int s = 0; s < 4; ++s) { float g[8], o[8]; ld8f(gpre + s * 512 + lane * 8, g);
; #pragma unroll
;                 for (int i = 0; i < 8; ++i) o[i] = v[s * 8 + i] * r2 * g[i];
;                 *(u32x4*)(hn + ro + s * 512) = pack8(o); }
	v_add_f32_e32 v62, v62, v63
	ds_bpermute_b32 v63, v29, v62
	s_waitcnt lgkmcnt(0)
	v_add_f32_e32 v62, v62, v63
	ds_bpermute_b32 v63, v30, v62
	s_waitcnt lgkmcnt(0)
	v_add_f32_e32 v62, v62, v63
	ds_bpermute_b32 v63, v31, v62
	s_waitcnt lgkmcnt(0)
	v_add_f32_e32 v62, v62, v63
	ds_bpermute_b32 v63, v32, v62
	s_waitcnt lgkmcnt(0)
	v_add_f32_e32 v62, v62, v63
	ds_bpermute_b32 v63, v33, v62
	s_waitcnt lgkmcnt(0)
	v_add_f32_e32 v62, v62, v63
	v_fmamk_f32 v62, v62, 0x3a000000, v209
	v_mul_f32_e32 v63, 0x4b800000, v62
	v_cmp_gt_f32_e32 vcc, s15, v62
	s_nop 1
	v_cndmask_b32_e32 v62, v62, v63, vcc
	v_rsq_f32_e32 v62, v62
	s_nop 0
	v_mul_f32_e32 v63, 0x45800000, v62
	v_cndmask_b32_e32 v62, v62, v63, vcc
	v_mul_f32_e32 v34, v34, v62
	v_mul_f32_e32 v35, v35, v62
	v_mul_f32_e32 v36, v36, v62
	v_mul_f32_e32 v37, v37, v62
	s_nop 0
	v_mul_f32_e32 v34, v156, v34
	v_mul_f32_e32 v35, v157, v35
	v_mul_f32_e32 v36, v158, v36
	v_mul_f32_e32 v37, v159, v37
	v_mul_f32_e32 v38, v38, v62
	v_mul_f32_e32 v39, v39, v62
	v_mul_f32_e32 v40, v40, v62
	v_mul_f32_e32 v41, v41, v62
	v_mul_f32_e32 v38, v152, v38
	v_mul_f32_e32 v39, v153, v39
	v_mul_f32_e32 v40, v154, v40
	v_mul_f32_e32 v41, v155, v41
	v_cvt_pk_bf16_f32 v34, v34, v35
	v_cvt_pk_bf16_f32 v35, v36, v37
	v_cvt_pk_bf16_f32 v36, v38, v39
	v_cvt_pk_bf16_f32 v37, v40, v41
	global_store_dwordx4 v[26:27], v[34:37], off
	s_nop 0
	v_mul_f32_e32 v42, v42, v62
	v_mul_f32_e32 v43, v43, v62
	v_mul_f32_e32 v44, v44, v62
	v_mul_f32_e32 v45, v45, v62
	v_mul_f32_e32 v46, v46, v62
	v_mul_f32_e32 v47, v47, v62
	v_mul_f32_e32 v48, v48, v62
	v_mul_f32_e32 v49, v49, v62
	v_mul_f32_e32 v11, v11, v62
	v_mul_f32_e32 v8, v8, v62
	v_mul_f32_e32 v9, v9, v62
	v_mul_f32_e32 v10, v10, v62
	v_mul_f32_e32 v3, v3, v62
	v_mul_f32_e32 v4, v4, v62
	v_mul_f32_e32 v5, v5, v62
	v_mul_f32_e32 v6, v6, v62
	v_mul_f32_e32 v7, v7, v62
	v_mul_f32_e32 v0, v0, v62
	v_mul_f32_e32 v1, v1, v62
	v_mul_f32_e32 v2, v2, v62
	s_nop 0
	v_mul_f32_e32 v34, v160, v42
	v_mul_f32_e32 v35, v161, v43
	v_mul_f32_e32 v36, v162, v44
	v_mul_f32_e32 v37, v163, v45
	s_nop 0
	v_mul_f32_e32 v38, v164, v46
	v_mul_f32_e32 v39, v165, v47
	v_mul_f32_e32 v40, v166, v48
	v_mul_f32_e32 v41, v167, v49
	v_cvt_pk_bf16_f32 v34, v34, v35
	v_cvt_pk_bf16_f32 v35, v36, v37
	v_cvt_pk_bf16_f32 v36, v38, v39
	v_cvt_pk_bf16_f32 v37, v40, v41
	global_store_dwordx4 v[26:27], v[34:37], off offset:1024
	s_nop 0
	v_mul_f32_e32 v42, v50, v62
	v_mul_f32_e32 v43, v51, v62
	v_mul_f32_e32 v44, v52, v62
	v_mul_f32_e32 v45, v53, v62
	s_nop 0
	v_mul_f32_e32 v34, v168, v42
	s_nop 0
	v_mul_f32_e32 v11, v175, v11
	v_mul_f32_e32 v35, v169, v43
	v_mul_f32_e32 v36, v170, v44
	v_mul_f32_e32 v37, v171, v45
	v_mul_f32_e32 v38, v172, v8
	v_mul_f32_e32 v39, v173, v9
	v_mul_f32_e32 v40, v174, v10
	v_cvt_pk_bf16_f32 v8, v34, v35
	v_cvt_pk_bf16_f32 v9, v36, v37
	v_cvt_pk_bf16_f32 v10, v38, v39
	v_cvt_pk_bf16_f32 v11, v40, v11
	global_store_dwordx4 v[26:27], v[8:11], off offset:2048
	s_nop 0
	s_nop 0
	v_mul_f32_e32 v4, v176, v4
	s_nop 0
	v_mul_f32_e32 v3, v183, v3
	v_mul_f32_e32 v5, v177, v5
	v_mul_f32_e32 v6, v178, v6
	v_mul_f32_e32 v7, v179, v7
	v_mul_f32_e32 v8, v180, v0
	v_mul_f32_e32 v9, v181, v1
	v_mul_f32_e32 v10, v182, v2
	v_cvt_pk_bf16_f32 v0, v4, v5
	v_cvt_pk_bf16_f32 v1, v6, v7
	v_cvt_pk_bf16_f32 v2, v8, v9
	v_cvt_pk_bf16_f32 v3, v10, v3
	global_store_dwordx4 v[26:27], v[0:3], off offset:3072
	v_lshl_add_u64 v[26:27], v[26:27], 0, s[30:31]
	s_cbranch_scc0 .LBB0_80

; __device__ __forceinline__ u32x4 pack8(const float* f) { u32x4 w; w.x = pk2(f[0], f[1]); w.y = pk2(f[2], f[3]); w.z = pk2(f[4], f[5]); w.w = pk2(f[6], f[7]); return w; }
; template <bool HAS_M, bool WRITE_X, bool WRITE_HN>
; __device__ __forceinline__ void seam_rows(const float* xin, const bf16_t* mb, const float* gpost, const float* gpre, float* xout, bf16_t* hn, int gw, int NGW, int lane) {
;     for (int row = gw; row < M; row += NGW) {
;         const size_t ro = (size_t)row * DM + lane * 8;
;         float v[32];
; #pragma unroll
;         for (int s = 0; s < 4; ++s) ld8f(xin + ro + s * 512, v + s * 8);
;         if (HAS_M) {
;             float mv[32]; float ss = 0.f;
; #pragma unroll
;             for (int s = 0; s < 4; ++s) unpack8(*(const u32x4*)(mb + ro + s * 512), mv + s * 8);
; #pragma unroll
;             for (int i = 0; i < 32; ++i) ss += mv[i] * mv[i];
;             const float r1 = rsqrtf(wave_sum(ss) * (1.f / 2048.f) + 1e-6f);
; #pragma unroll
;             for (int s = 0; s < 4; ++s) { float g[8]; ld8f(gpost + s * 512 + lane * 8, g);
; #pragma unroll
;                 for (int i = 0; i < 8; ++i) v[s * 8 + i] += mv[s * 8 + i] * r1 * g[i]; }
;         }
;         if (WRITE_X) {
; #pragma unroll
;             for (int s = 0; s < 4; ++s) { *(f32x4*)(xout + ro + s * 512) = (f32x4){v[s * 8], v[s * 8 + 1], v[s * 8 + 2], v[s * 8 + 3]}; *(f32x4*)(xout + ro + s * 512 + 4) = (f32x4){v[s * 8 + 4], v[s * 8 + 5], v[s * 8 + 6], v[s * 8 + 7]}; }
;         }
;         if (WRITE_HN) {
;             float ss = 0.f;
; #pragma unroll
;             for (int i = 0; i < 32; ++i) ss += v[i] * v[i];
;             const float r2 = rsqrtf(wave_sum(ss) * (1.f / 2048.f) + 1e-6f);
; #pragma unroll
;             for (int s = 0; s < 4; ++s) { float g[8], o[8]; ld8f(gpre + s * 512 + lane * 8, g);
; #pragma unroll
;                 for (int i = 0; i < 8; ++i) o[i] = v[s * 8 + i] * r2 * g[i];
;                 *(u32x4*)(hn + ro + s * 512) = pack8(o); }
.LBB0_414:
	s_or_b64 exec, exec, s[12:13]
	s_cmpk_gt_i32 s10, 0x3fff
	s_cbranch_scc1 .LBB0_417
	v_cmp_lt_i32_e32 vcc, v213, v212
	s_waitcnt lgkmcnt(0)
	s_load_dwordx2 s[8:9], s[64:65], 0xf8
	s_load_dwordx2 s[12:13], s[64:65], 0x8
	s_load_dwordx2 s[18:19], s[64:65], 0x20
	v_cndmask_b32_e32 v0, v211, v213, vcc
	v_cmp_lt_i32_e32 vcc, v210, v212
	v_lshlrev_b32_e32 v28, 2, v0
	v_lshlrev_b32_e32 v128, 5, v42
	v_cndmask_b32_e32 v0, v211, v210, vcc
	v_lshlrev_b32_e32 v29, 2, v0
	v_xor_b32_e32 v0, 4, v211
	v_cmp_lt_i32_e32 vcc, v0, v212
	s_waitcnt lgkmcnt(0)
	v_lshl_add_u64 v[12:13], s[18:19], 0, v[128:129]
	s_ashr_i32 s2, s26, 31
	v_cndmask_b32_e32 v0, v211, v0, vcc
	v_lshlrev_b32_e32 v30, 2, v0
	v_xor_b32_e32 v0, 8, v211
	v_cmp_lt_i32_e32 vcc, v0, v212
	s_mov_b64 s[28:29], 0x1000
	v_lshl_add_u64 v[16:17], v[12:13], 0, s[28:29]
	v_cndmask_b32_e32 v0, v211, v0, vcc
	v_lshlrev_b32_e32 v31, 2, v0
	v_xor_b32_e32 v0, 16, v211
	v_cmp_lt_i32_e32 vcc, v0, v212
	s_nop 1
	v_cndmask_b32_e32 v0, v211, v0, vcc
	v_cmp_lt_i32_e32 vcc, v218, v212
	v_lshlrev_b32_e32 v32, 2, v0
	s_nop 0
	v_cndmask_b32_e32 v0, v211, v218, vcc
	v_lshlrev_b32_e32 v33, 2, v0
	v_lshl_add_u64 v[0:1], s[12:13], 0, v[128:129]
	s_mov_b64 s[12:13], 0x2000
	v_lshl_add_u64 v[14:15], v[0:1], 0, s[12:13]
	s_mov_b64 s[12:13], 0x1800
	v_lshl_add_u64 v[18:19], v[12:13], 0, s[12:13]
	s_mov_b64 s[12:13], 0x3000
	v_lshl_add_u64 v[20:21], v[0:1], 0, s[12:13]
	s_mov_b64 s[12:13], 0x3800
	v_lshl_add_u64 v[22:23], v[0:1], 0, s[12:13]
	s_ashr_i32 s13, s17, 31
	s_add_u32 s12, s26, s17
	s_addc_u32 s13, s2, s13
	s_lshl_b64 s[18:19], s[12:13], 13
	s_add_u32 s8, s8, s18
	s_addc_u32 s9, s9, s19
	s_ashr_i32 s17, s16, 31
	v_lshl_add_u64 v[0:1], s[8:9], 0, v[128:129]
	s_lshl_b64 s[8:9], s[16:17], 13
	s_lshl_b64 s[12:13], s[12:13], 12
	s_add_u32 s12, s83, s12
	v_lshlrev_b32_e32 v128, 4, v42
	s_addc_u32 s13, s93, s13
	v_lshl_add_u64 v[24:25], v[0:1], 0, s[28:29]
	v_lshl_add_u64 v[26:27], s[12:13], 0, v[128:129]
	s_lshl_b64 s[12:13], s[16:17], 12
	global_load_dwordx4 v[152:155], v[14:15], off offset:16
	global_load_dwordx4 v[156:159], v[14:15], off
	global_load_dwordx4 v[160:163], v[14:15], off offset:2048
	global_load_dwordx4 v[164:167], v[14:15], off offset:2064
	global_load_dwordx4 v[168:171], v[20:21], off
	global_load_dwordx4 v[172:175], v[20:21], off offset:16
	global_load_dwordx4 v[176:179], v[22:23], off
	global_load_dwordx4 v[180:183], v[22:23], off offset:16
.LBB0_416:
	v_add_co_u32_e32 v0, vcc, 0xefa00000, v26
	s_add_i32 s10, s10, s16
	s_nop 0
	v_addc_co_u32_e32 v1, vcc, -1, v27, vcc
	global_load_dwordx4 v[8:11], v[0:1], off
	v_add_co_u32_e32 v0, vcc, 0xefa01000, v26
	s_cmpk_gt_i32 s10, 0x3fff
	s_nop 0
	v_addc_co_u32_e32 v1, vcc, -1, v27, vcc
	global_load_dwordx4 v[34:37], v[0:1], off offset:-3072
	global_load_dwordx4 v[38:41], v[0:1], off offset:-2048
	global_load_dwordx4 v[42:45], v[0:1], off offset:-1024
	global_load_dwordx4 v[46:49], v[24:25], off offset:-4080
	global_load_dwordx4 v[50:53], v[24:25], off offset:-4096
	global_load_dwordx4 v[54:57], v[24:25], off offset:-2032
	global_load_dwordx4 v[58:61], v[24:25], off offset:-2048
	global_load_dwordx4 v[4:7], v[24:25], off offset:16
	global_load_dwordx4 v[62:65], v[24:25], off
	global_load_dwordx4 v[0:3], v[24:25], off offset:2064
	global_load_dwordx4 v[66:69], v[24:25], off offset:2048
	global_load_dwordx4 v[70:73], v[12:13], off offset:16
	global_load_dwordx4 v[74:77], v[12:13], off
	global_load_dwordx4 v[78:81], v[12:13], off offset:2064
	global_load_dwordx4 v[82:85], v[12:13], off offset:2048
	global_load_dwordx4 v[86:89], v[16:17], off offset:16
	global_load_dwordx4 v[90:93], v[16:17], off
	global_load_dwordx4 v[94:97], v[18:19], off offset:16
	global_load_dwordx4 v[98:101], v[18:19], off
	s_waitcnt vmcnt(18)
	v_lshlrev_b32_e32 v114, 16, v34
	v_and_b32_e32 v115, 0xffff0000, v34
	v_pk_mul_f32 v[126:127], v[114:115], v[114:115]
	v_lshlrev_b32_e32 v34, 16, v35
	v_and_b32_e32 v35, 0xffff0000, v35
	v_pk_mul_f32 v[130:131], v[34:35], v[34:35]
	v_lshlrev_b32_e32 v116, 16, v36
	v_and_b32_e32 v117, 0xffff0000, v36
	v_pk_mul_f32 v[132:133], v[116:117], v[116:117]
	v_lshlrev_b32_e32 v36, 16, v37
	v_and_b32_e32 v37, 0xffff0000, v37
	v_pk_mul_f32 v[134:135], v[36:37], v[36:37]
	v_lshlrev_b32_e32 v102, 16, v8
	v_and_b32_e32 v103, 0xffff0000, v8
	v_lshlrev_b32_e32 v8, 16, v9
	v_and_b32_e32 v9, 0xffff0000, v9
	v_pk_mul_f32 v[106:107], v[102:103], v[102:103]
	v_pk_mul_f32 v[108:109], v[8:9], v[8:9]
	v_add_f32_e32 v106, v106, v107
	v_lshlrev_b32_e32 v104, 16, v10
	v_and_b32_e32 v105, 0xffff0000, v10
	v_add_f32_e32 v106, v108, v106
	v_pk_mul_f32 v[110:111], v[104:105], v[104:105]
	v_add_f32_e32 v106, v109, v106
	v_lshlrev_b32_e32 v10, 16, v11
	v_and_b32_e32 v11, 0xffff0000, v11
	v_add_f32_e32 v106, v110, v106
	v_pk_mul_f32 v[112:113], v[10:11], v[10:11]
	v_add_f32_e32 v106, v111, v106
	v_add_f32_e32 v106, v112, v106
	v_add_f32_e32 v106, v113, v106
	v_add_f32_e32 v106, v126, v106
	v_add_f32_e32 v106, v127, v106
	v_add_f32_e32 v106, v130, v106
	v_add_f32_e32 v106, v131, v106
	v_add_f32_e32 v106, v132, v106
	v_add_f32_e32 v106, v133, v106
	s_waitcnt vmcnt(17)
	v_lshlrev_b32_e32 v118, 16, v38
	v_and_b32_e32 v119, 0xffff0000, v38
	v_add_f32_e32 v106, v134, v106
	v_pk_mul_f32 v[136:137], v[118:119], v[118:119]
	v_add_f32_e32 v106, v135, v106
	v_lshlrev_b32_e32 v38, 16, v39
	v_and_b32_e32 v39, 0xffff0000, v39
	v_add_f32_e32 v106, v136, v106
	v_pk_mul_f32 v[138:139], v[38:39], v[38:39]
	v_add_f32_e32 v106, v137, v106
	v_lshlrev_b32_e32 v120, 16, v40
	v_and_b32_e32 v121, 0xffff0000, v40
	v_add_f32_e32 v106, v138, v106
	v_pk_mul_f32 v[140:141], v[120:121], v[120:121]
	v_add_f32_e32 v106, v139, v106
	v_lshlrev_b32_e32 v40, 16, v41
	v_and_b32_e32 v41, 0xffff0000, v41
	v_add_f32_e32 v106, v140, v106
	v_pk_mul_f32 v[142:143], v[40:41], v[40:41]
	v_add_f32_e32 v106, v141, v106
	s_waitcnt vmcnt(16)
; template <bool HAS_M, bool WRITE_X, bool WRITE_HN>
; __device__ __forceinline__ void seam_rows(const float* xin, const bf16_t* mb, const float* gpost, const float* gpre, float* xout, bf16_t* hn, int gw, int NGW, int lane) {
;     ...
;         if (HAS_M) {
;             float mv[32]; float ss = 0.f;
; #pragma unroll
;             for (int s = 0; s < 4; ++s) unpack8(*(const u32x4*)(mb + ro + s * 512), mv + s * 8);
; #pragma unroll
;             for (int i = 0; i < 32; ++i) ss += mv[i] * mv[i];
;             const float r1 = rsqrtf(wave_sum(ss) * (1.f / 2048.f) + 1e-6f);
; #pragma unroll
;             for (int s = 0; s < 4; ++s) { float g[8]; ld8f(gpost + s * 512 + lane * 8, g);
; #pragma unroll
;                 for (int i = 0; i < 8; ++i) v[s * 8 + i] += mv[s * 8 + i] * r1 * g[i]; }
;         }
;         if (WRITE_X) {
; #pragma unroll
;             for (int s = 0; s < 4; ++s) { *(f32x4*)(xout + ro + s * 512) = (f32x4){v[s * 8], v[s * 8 + 1], v[s * 8 + 2], v[s * 8 + 3]}; *(f32x4*)(xout + ro + s * 512 + 4) = (f32x4){v[s * 8 + 4], v[s * 8 + 5], v[s * 8 + 6], v[s * 8 + 7]}; }
;         }
;         if (WRITE_HN) {
;             float ss = 0.f;
; #pragma unroll
;             for (int i = 0; i < 32; ++i) ss += v[i] * v[i];
;             const float r2 = rsqrtf(wave_sum(ss) * (1.f / 2048.f) + 1e-6f);
	v_lshlrev_b32_e32 v122, 16, v42
	v_and_b32_e32 v123, 0xffff0000, v42
	v_add_f32_e32 v106, v142, v106
	v_pk_mul_f32 v[144:145], v[122:123], v[122:123]
	v_add_f32_e32 v106, v143, v106
	v_lshlrev_b32_e32 v42, 16, v43
	v_and_b32_e32 v43, 0xffff0000, v43
	v_add_f32_e32 v106, v144, v106
	v_pk_mul_f32 v[146:147], v[42:43], v[42:43]
	v_add_f32_e32 v106, v145, v106
	v_lshlrev_b32_e32 v124, 16, v44
	v_and_b32_e32 v125, 0xffff0000, v44
	v_add_f32_e32 v106, v146, v106
	v_pk_mul_f32 v[148:149], v[124:125], v[124:125]
	v_add_f32_e32 v106, v147, v106
	v_lshlrev_b32_e32 v44, 16, v45
	v_and_b32_e32 v45, 0xffff0000, v45
	v_add_f32_e32 v106, v148, v106
	v_pk_mul_f32 v[150:151], v[44:45], v[44:45]
	v_add_f32_e32 v106, v149, v106
	v_add_f32_e32 v106, v150, v106
	v_add_f32_e32 v106, v151, v106
	ds_bpermute_b32 v107, v28, v106
	s_waitcnt lgkmcnt(0)
	v_add_f32_e32 v106, v106, v107
	ds_bpermute_b32 v107, v29, v106
	s_waitcnt lgkmcnt(0)
	v_add_f32_e32 v106, v106, v107
	ds_bpermute_b32 v107, v30, v106
	s_waitcnt lgkmcnt(0)
	v_add_f32_e32 v106, v106, v107
	ds_bpermute_b32 v107, v31, v106
	s_waitcnt lgkmcnt(0)
	v_add_f32_e32 v106, v106, v107
	ds_bpermute_b32 v107, v32, v106
	s_waitcnt lgkmcnt(0)
	v_add_f32_e32 v106, v106, v107
	ds_bpermute_b32 v107, v33, v106
	s_waitcnt lgkmcnt(0)
	v_add_f32_e32 v106, v106, v107
	v_fmamk_f32 v106, v106, 0x3a000000, v209
	v_mul_f32_e32 v107, 0x4b800000, v106
	v_cmp_gt_f32_e32 vcc, s15, v106
	s_nop 1
	v_cndmask_b32_e32 v106, v106, v107, vcc
	v_rsq_f32_e32 v106, v106
	s_nop 0
	v_mul_f32_e32 v107, 0x45800000, v106
	v_cndmask_b32_e32 v106, v106, v107, vcc
	v_pk_mul_f32 v[102:103], v[106:107], v[102:103] op_sel_hi:[0,1]
	v_pk_mul_f32 v[8:9], v[106:107], v[8:9] op_sel_hi:[0,1]
	v_pk_mul_f32 v[104:105], v[106:107], v[104:105] op_sel_hi:[0,1]
	v_pk_mul_f32 v[110:111], v[106:107], v[34:35] op_sel_hi:[0,1]
	v_pk_mul_f32 v[112:113], v[106:107], v[116:117] op_sel_hi:[0,1]
	s_waitcnt vmcnt(6)
	v_pk_fma_f32 v[34:35], v[74:75], v[102:103], v[50:51]
	v_pk_mul_f32 v[10:11], v[106:107], v[10:11] op_sel_hi:[0,1]
	v_pk_mul_f32 v[108:109], v[106:107], v[114:115] op_sel_hi:[0,1]
	v_pk_mul_f32 v[114:115], v[106:107], v[36:37] op_sel_hi:[0,1]
	v_pk_mul_f32 v[116:117], v[106:107], v[118:119] op_sel_hi:[0,1]
	v_pk_mul_f32 v[118:119], v[106:107], v[38:39] op_sel_hi:[0,1]
	v_pk_mul_f32 v[120:121], v[106:107], v[120:121] op_sel_hi:[0,1]
	v_pk_mul_f32 v[126:127], v[106:107], v[40:41] op_sel_hi:[0,1]
	v_pk_mul_f32 v[122:123], v[106:107], v[122:123] op_sel_hi:[0,1]
	v_pk_mul_f32 v[130:131], v[106:107], v[42:43] op_sel_hi:[0,1]
	v_pk_mul_f32 v[124:125], v[106:107], v[124:125] op_sel_hi:[0,1]
	v_pk_mul_f32 v[106:107], v[106:107], v[44:45] op_sel_hi:[0,1]
	v_pk_fma_f32 v[36:37], v[76:77], v[8:9], v[52:53]
	v_pk_fma_f32 v[38:39], v[70:71], v[104:105], v[46:47]
	s_waitcnt vmcnt(5)
	v_pk_fma_f32 v[46:47], v[78:79], v[112:113], v[54:55]
	v_pk_mul_f32 v[54:55], v[34:35], v[34:35]
	v_pk_fma_f32 v[40:41], v[72:73], v[10:11], v[48:49]
	s_waitcnt vmcnt(4)
	v_pk_fma_f32 v[42:43], v[82:83], v[108:109], v[58:59]
	v_pk_fma_f32 v[44:45], v[84:85], v[110:111], v[60:61]
	v_pk_fma_f32 v[48:49], v[80:81], v[114:115], v[56:57]
	s_waitcnt vmcnt(2)
	v_pk_fma_f32 v[50:51], v[90:91], v[116:117], v[62:63]
	v_pk_fma_f32 v[52:53], v[92:93], v[118:119], v[64:65]
	v_pk_fma_f32 v[8:9], v[86:87], v[120:121], v[4:5]
	v_pk_fma_f32 v[10:11], v[88:89], v[126:127], v[6:7]
	s_waitcnt vmcnt(0)
	v_pk_fma_f32 v[4:5], v[98:99], v[122:123], v[66:67]
	v_pk_fma_f32 v[6:7], v[100:101], v[130:131], v[68:69]
	v_pk_fma_f32 v[0:1], v[94:95], v[124:125], v[0:1]
	v_pk_fma_f32 v[2:3], v[96:97], v[106:107], v[2:3]
	global_store_dwordx4 v[24:25], v[34:37], off offset:-4096
	global_store_dwordx4 v[24:25], v[38:41], off offset:-4080
	global_store_dwordx4 v[24:25], v[42:45], off offset:-2048
	global_store_dwordx4 v[24:25], v[46:49], off offset:-2032
	global_store_dwordx4 v[24:25], v[50:53], off
	global_store_dwordx4 v[24:25], v[8:11], off offset:16
	global_store_dwordx4 v[24:25], v[4:7], off offset:2048
	global_store_dwordx4 v[24:25], v[0:3], off offset:2064
	v_pk_mul_f32 v[62:63], v[36:37], v[36:37]
	v_add_f32_e32 v54, v54, v55
	v_add_f32_e32 v62, v62, v54
	v_pk_mul_f32 v[64:65], v[38:39], v[38:39]
	v_add_f32_e32 v62, v63, v62
	v_add_f32_e32 v62, v64, v62
	v_pk_mul_f32 v[66:67], v[40:41], v[40:41]
	v_add_f32_e32 v62, v65, v62
	v_add_f32_e32 v62, v66, v62
	v_pk_mul_f32 v[68:69], v[42:43], v[42:43]
	v_add_f32_e32 v62, v67, v62
	v_add_f32_e32 v62, v68, v62
	v_pk_mul_f32 v[70:71], v[44:45], v[44:45]
	v_add_f32_e32 v62, v69, v62
	v_add_f32_e32 v62, v70, v62
	v_pk_mul_f32 v[72:73], v[46:47], v[46:47]
	v_add_f32_e32 v62, v71, v62
	v_add_f32_e32 v62, v72, v62
	v_pk_mul_f32 v[74:75], v[48:49], v[48:49]
	v_add_f32_e32 v62, v73, v62
	v_add_f32_e32 v62, v74, v62
	v_pk_mul_f32 v[76:77], v[50:51], v[50:51]
	v_add_f32_e32 v62, v75, v62
	v_add_f32_e32 v62, v76, v62
	v_pk_mul_f32 v[78:79], v[52:53], v[52:53]
	v_add_f32_e32 v62, v77, v62
	v_add_f32_e32 v62, v78, v62
	v_pk_mul_f32 v[80:81], v[8:9], v[8:9]
	v_add_f32_e32 v62, v79, v62
	v_add_f32_e32 v62, v80, v62
	v_pk_mul_f32 v[82:83], v[10:11], v[10:11]
	v_add_f32_e32 v62, v81, v62
	v_add_f32_e32 v62, v82, v62
	v_pk_mul_f32 v[84:85], v[4:5], v[4:5]
	v_add_f32_e32 v62, v83, v62
	v_add_f32_e32 v62, v84, v62
	v_pk_mul_f32 v[86:87], v[6:7], v[6:7]
	v_add_f32_e32 v62, v85, v62
	v_add_f32_e32 v62, v86, v62
	v_pk_mul_f32 v[88:89], v[0:1], v[0:1]
	v_add_f32_e32 v62, v87, v62
	v_add_f32_e32 v62, v88, v62
	v_pk_mul_f32 v[90:91], v[2:3], v[2:3]
	v_add_f32_e32 v62, v89, v62
	v_add_f32_e32 v62, v90, v62
	v_add_f32_e32 v62, v91, v62
	ds_bpermute_b32 v63, v28, v62
	v_lshl_add_u64 v[24:25], v[24:25], 0, s[8:9]
	s_waitcnt lgkmcnt(0)
; __device__ __forceinline__ u32x4 pack8(const float* f) { u32x4 w; w.x = pk2(f[0], f[1]); w.y = pk2(f[2], f[3]); w.z = pk2(f[4], f[5]); w.w = pk2(f[6], f[7]); return w; }
; template <bool HAS_M, bool WRITE_X, bool WRITE_HN>
; __device__ __forceinline__ void seam_rows(const float* xin, const bf16_t* mb, const float* gpost, const float* gpre, float* xout, bf16_t* hn, int gw, int NGW, int lane) {
;     ...
;         if (WRITE_HN) {
;             float ss = 0.f;
; #pragma unroll
;             for (int i = 0; i < 32; ++i) ss += v[i] * v[i];
;             const float r2 = rsqrtf(wave_sum(ss) * (1.f / 2048.f) + 1e-6f);
; #pragma unroll
;             for (int s = 0; s < 4; ++s) { float g[8], o[8]; ld8f(gpre + s * 512 + lane * 8, g);
; #pragma unroll
;                 for (int i = 0; i < 8; ++i) o[i] = v[s * 8 + i] * r2 * g[i];
;                 *(u32x4*)(hn + ro + s * 512) = pack8(o); }
	v_add_f32_e32 v62, v62, v63
	ds_bpermute_b32 v63, v29, v62
	s_waitcnt lgkmcnt(0)
	v_add_f32_e32 v62, v62, v63
	ds_bpermute_b32 v63, v30, v62
	s_waitcnt lgkmcnt(0)
	v_add_f32_e32 v62, v62, v63
	ds_bpermute_b32 v63, v31, v62
	s_waitcnt lgkmcnt(0)
	v_add_f32_e32 v62, v62, v63
	ds_bpermute_b32 v63, v32, v62
	s_waitcnt lgkmcnt(0)
	v_add_f32_e32 v62, v62, v63
	ds_bpermute_b32 v63, v33, v62
	s_waitcnt lgkmcnt(0)
	v_add_f32_e32 v62, v62, v63
	v_fmamk_f32 v62, v62, 0x3a000000, v209
	v_mul_f32_e32 v63, 0x4b800000, v62
	v_cmp_gt_f32_e32 vcc, s15, v62
	s_nop 1
	v_cndmask_b32_e32 v62, v62, v63, vcc
	v_rsq_f32_e32 v62, v62
	s_nop 0
	v_mul_f32_e32 v63, 0x45800000, v62
	v_cndmask_b32_e32 v62, v62, v63, vcc
	v_mul_f32_e32 v34, v34, v62
	v_mul_f32_e32 v35, v35, v62
	v_mul_f32_e32 v36, v36, v62
	v_mul_f32_e32 v37, v37, v62
	s_nop 0
	v_mul_f32_e32 v34, v156, v34
	v_mul_f32_e32 v35, v157, v35
	v_mul_f32_e32 v36, v158, v36
	v_mul_f32_e32 v37, v159, v37
	v_mul_f32_e32 v38, v38, v62
	v_mul_f32_e32 v39, v39, v62
	v_mul_f32_e32 v40, v40, v62
	v_mul_f32_e32 v41, v41, v62
	v_mul_f32_e32 v38, v152, v38
	v_mul_f32_e32 v39, v153, v39
	v_mul_f32_e32 v40, v154, v40
	v_mul_f32_e32 v41, v155, v41
	v_cvt_pk_bf16_f32 v34, v34, v35
	v_cvt_pk_bf16_f32 v35, v36, v37
	v_cvt_pk_bf16_f32 v36, v38, v39
	v_cvt_pk_bf16_f32 v37, v40, v41
	global_store_dwordx4 v[26:27], v[34:37], off
	s_nop 0
	v_mul_f32_e32 v42, v42, v62
	v_mul_f32_e32 v43, v43, v62
	v_mul_f32_e32 v44, v44, v62
	v_mul_f32_e32 v45, v45, v62
	v_mul_f32_e32 v46, v46, v62
	v_mul_f32_e32 v47, v47, v62
	v_mul_f32_e32 v48, v48, v62
	v_mul_f32_e32 v49, v49, v62
	v_mul_f32_e32 v11, v11, v62
	v_mul_f32_e32 v8, v8, v62
	v_mul_f32_e32 v9, v9, v62
	v_mul_f32_e32 v10, v10, v62
	v_mul_f32_e32 v3, v3, v62
	v_mul_f32_e32 v4, v4, v62
	v_mul_f32_e32 v5, v5, v62
	v_mul_f32_e32 v6, v6, v62
	v_mul_f32_e32 v7, v7, v62
	v_mul_f32_e32 v0, v0, v62
	v_mul_f32_e32 v1, v1, v62
	v_mul_f32_e32 v2, v2, v62
	s_nop 0
	v_mul_f32_e32 v34, v160, v42
	v_mul_f32_e32 v35, v161, v43
	v_mul_f32_e32 v36, v162, v44
	v_mul_f32_e32 v37, v163, v45
	s_nop 0
	v_mul_f32_e32 v38, v164, v46
	v_mul_f32_e32 v39, v165, v47
	v_mul_f32_e32 v40, v166, v48
	v_mul_f32_e32 v41, v167, v49
	v_cvt_pk_bf16_f32 v34, v34, v35
	v_cvt_pk_bf16_f32 v35, v36, v37
	v_cvt_pk_bf16_f32 v36, v38, v39
	v_cvt_pk_bf16_f32 v37, v40, v41
	global_store_dwordx4 v[26:27], v[34:37], off offset:1024
	s_nop 0
	v_mul_f32_e32 v42, v50, v62
	v_mul_f32_e32 v43, v51, v62
	v_mul_f32_e32 v44, v52, v62
	v_mul_f32_e32 v45, v53, v62
	s_nop 0
	v_mul_f32_e32 v34, v168, v42
	s_nop 0
	v_mul_f32_e32 v11, v175, v11
	v_mul_f32_e32 v35, v169, v43
	v_mul_f32_e32 v36, v170, v44
	v_mul_f32_e32 v37, v171, v45
	v_mul_f32_e32 v38, v172, v8
	v_mul_f32_e32 v39, v173, v9
	v_mul_f32_e32 v40, v174, v10
	v_cvt_pk_bf16_f32 v8, v34, v35
	v_cvt_pk_bf16_f32 v9, v36, v37
	v_cvt_pk_bf16_f32 v10, v38, v39
	v_cvt_pk_bf16_f32 v11, v40, v11
	global_store_dwordx4 v[26:27], v[8:11], off offset:2048
	s_nop 0
	s_nop 0
	v_mul_f32_e32 v4, v176, v4
	s_nop 0
	v_mul_f32_e32 v3, v183, v3
	v_mul_f32_e32 v5, v177, v5
	v_mul_f32_e32 v6, v178, v6
	v_mul_f32_e32 v7, v179, v7
	v_mul_f32_e32 v8, v180, v0
	v_mul_f32_e32 v9, v181, v1
	v_mul_f32_e32 v10, v182, v2
	v_cvt_pk_bf16_f32 v0, v4, v5
	v_cvt_pk_bf16_f32 v1, v6, v7
	v_cvt_pk_bf16_f32 v2, v8, v9
	v_cvt_pk_bf16_f32 v3, v10, v3
	global_store_dwordx4 v[26:27], v[0:3], off offset:3072
	v_lshl_add_u64 v[26:27], v[26:27], 0, s[12:13]
	s_cbranch_scc0 .LBB0_416

; template <bool HAS_M, bool WRITE_X, bool WRITE_HN>
; __device__ __forceinline__ void seam_rows(const float* xin, const bf16_t* mb, const float* gpost, const float* gpre, float* xout, bf16_t* hn, int gw, int NGW, int lane) {
;     for (int row = gw; row < M; row += NGW) {
;         const size_t ro = (size_t)row * DM + lane * 8;
;         float v[32];
; #pragma unroll
;         for (int s = 0; s < 4; ++s) ld8f(xin + ro + s * 512, v + s * 8);
;         if (HAS_M) {
;             float mv[32]; float ss = 0.f;
; #pragma unroll
;             for (int s = 0; s < 4; ++s) unpack8(*(const u32x4*)(mb + ro + s * 512), mv + s * 8);
; #pragma unroll
;             for (int i = 0; i < 32; ++i) ss += mv[i] * mv[i];
;             const float r1 = rsqrtf(wave_sum(ss) * (1.f / 2048.f) + 1e-6f);
; #pragma unroll
;             for (int s = 0; s < 4; ++s) { float g[8]; ld8f(gpost + s * 512 + lane * 8, g);
; #pragma unroll
;                 for (int i = 0; i < 8; ++i) v[s * 8 + i] += mv[s * 8 + i] * r1 * g[i]; }
;         }
;         if (WRITE_X) {
; #pragma unroll
;             for (int s = 0; s < 4; ++s) { *(f32x4*)(xout + ro + s * 512) = (f32x4){v[s * 8], v[s * 8 + 1], v[s * 8 + 2], v[s * 8 + 3]}; *(f32x4*)(xout + ro + s * 512 + 4) = (f32x4){v[s * 8 + 4], v[s * 8 + 5], v[s * 8 + 6], v[s * 8 + 7]}; }
;         }
;         if (WRITE_HN) {
;             float ss = 0.f;
; #pragma unroll
;             for (int i = 0; i < 32; ++i) ss += v[i] * v[i];
;             const float r2 = rsqrtf(wave_sum(ss) * (1.f / 2048.f) + 1e-6f);
; #pragma unroll
;             for (int s = 0; s < 4; ++s) { float g[8], o[8]; ld8f(gpre + s * 512 + lane * 8, g);
.LBB0_463:
	s_andn2_b64 vcc, exec, s[8:9]
	s_cbranch_vccnz .LBB0_468
	s_waitcnt vmcnt(0)
	v_mov_b32_e32 v0, v208
	s_lshl_b32 s2, s23, 3
	v_readfirstlane_b32 s7, v0
	s_ashr_i32 s8, s7, 6
	s_add_i32 s7, s8, s2
	s_cmpk_gt_i32 s7, 0x3fff
	s_cbranch_scc1 .LBB0_468
	v_cmp_lt_i32_e32 vcc, v213, v212
	s_load_dwordx2 s[26:27], s[64:65], 0xf8
	s_load_dwordx2 s[12:13], s[64:65], 0x0
	s_load_dwordx4 s[28:31], s[64:65], 0x10
	v_cndmask_b32_e32 v1, v211, v213, vcc
	v_cmp_lt_i32_e32 vcc, v210, v212
	v_lshlrev_b32_e32 v62, 2, v1
	s_mov_b64 s[18:19], 0x1000
	v_cndmask_b32_e32 v1, v211, v210, vcc
	v_lshlrev_b32_e32 v63, 2, v1
	v_xor_b32_e32 v1, 4, v211
	v_cmp_lt_i32_e32 vcc, v1, v212
	s_ashr_i32 s9, s8, 31
	s_ashr_i32 s10, s2, 31
	v_cndmask_b32_e32 v1, v211, v1, vcc
	v_lshlrev_b32_e32 v64, 2, v1
	v_xor_b32_e32 v1, 8, v211
	v_cmp_lt_i32_e32 vcc, v1, v212
	s_mov_b32 s6, s17
	s_mov_b64 s[34:35], 0x1800
	v_cndmask_b32_e32 v1, v211, v1, vcc
	v_lshlrev_b32_e32 v65, 2, v1
	v_xor_b32_e32 v1, 16, v211
	v_cmp_lt_i32_e32 vcc, v1, v212
	s_nop 1
	v_cndmask_b32_e32 v1, v211, v1, vcc
	v_cmp_lt_i32_e32 vcc, v218, v212
	v_lshlrev_b32_e32 v66, 2, v1
	s_nop 0
	v_cndmask_b32_e32 v1, v211, v218, vcc
	v_lshlrev_b32_e32 v67, 2, v1
	v_lshlrev_b32_e32 v1, 5, v0
	v_and_b32_e32 v128, 0x7e0, v1
	s_waitcnt lgkmcnt(0)
	v_lshl_add_u64 v[40:41], s[28:29], 0, v[128:129]
	v_lshl_add_u64 v[42:43], s[30:31], 0, v[128:129]
	v_lshl_add_u64 v[44:45], v[40:41], 0, s[18:19]
	v_lshl_add_u64 v[48:49], v[42:43], 0, s[18:19]
	s_add_u32 s18, s8, s2
	s_addc_u32 s19, s9, s10
	s_lshl_b64 s[28:29], s[18:19], 13
	s_add_u32 s8, s12, s28
	s_addc_u32 s9, s13, s29
	s_ashr_i32 s17, s16, 31
	s_lshl_b64 s[12:13], s[16:17], 13
	s_lshl_b64 s[18:19], s[18:19], 12
	v_and_b32_e32 v0, 63, v0
	s_add_u32 s18, s4, s18
	v_lshlrev_b32_e32 v128, 5, v0
	v_lshlrev_b32_e32 v0, 4, v0
	v_mov_b32_e32 v1, v129
	s_addc_u32 s19, s5, s19
	v_lshl_add_u64 v[0:1], s[18:19], 0, v[0:1]
	s_mov_b64 s[18:19], 0xa100c00
	v_lshl_add_u64 v[52:53], v[0:1], 0, s[18:19]
	s_lshl_b64 s[18:19], s[16:17], 12
	s_add_u32 s30, s26, s28
	v_lshl_add_u64 v[46:47], v[40:41], 0, s[34:35]
	v_lshl_add_u64 v[50:51], v[42:43], 0, s[34:35]
	s_addc_u32 s31, s27, s29
	s_mov_b64 s[26:27], 0x1000
	global_load_dwordx4 v[152:155], v[42:43], off offset:16
	global_load_dwordx4 v[156:159], v[42:43], off
	global_load_dwordx4 v[160:163], v[42:43], off offset:2064
	global_load_dwordx4 v[164:167], v[42:43], off offset:2048
	global_load_dwordx4 v[168:171], v[48:49], off offset:16
	global_load_dwordx4 v[172:175], v[48:49], off
	global_load_dwordx4 v[176:179], v[50:51], off offset:16
	global_load_dwordx4 v[180:183], v[50:51], off
.LBB0_466:
	s_nop 0
	v_lshl_add_u64 v[0:1], s[8:9], 0, v[128:129]
	v_add_co_u32_e32 v4, vcc, 0x1000, v0
	global_load_dwordx4 v[20:23], v[0:1], off offset:16
	global_load_dwordx4 v[24:27], v[0:1], off
	global_load_dwordx4 v[12:15], v[0:1], off offset:2064
	global_load_dwordx4 v[16:19], v[0:1], off offset:2048
	v_lshl_add_u64 v[2:3], v[0:1], 0, s[26:27]
	v_addc_co_u32_e32 v5, vcc, 0, v1, vcc
	v_lshl_add_u64 v[0:1], v[0:1], 0, s[34:35]
	global_load_dwordx4 v[32:35], v[4:5], off
	global_load_dwordx4 v[8:11], v[2:3], off offset:16
	s_nop 0
	global_load_dwordx4 v[4:7], v[4:5], off offset:2048
	s_nop 0
	global_load_dwordx4 v[0:3], v[0:1], off offset:16
	s_nop 0
	global_load_dwordx4 v[58:61], v[52:53], off offset:-3072
	global_load_dwordx4 v[68:71], v[52:53], off offset:-2048
	global_load_dwordx4 v[72:75], v[52:53], off offset:-1024
	global_load_dwordx4 v[76:79], v[52:53], off
	global_load_dwordx4 v[36:39], v[40:41], off offset:16
	global_load_dwordx4 v[28:31], v[40:41], off
	global_load_dwordx4 v[80:83], v[40:41], off offset:2064
	global_load_dwordx4 v[84:87], v[40:41], off offset:2048
	s_movk_i32 s2, 0x1000
	s_add_i32 s7, s7, s16
	s_add_u32 s8, s8, s12
	s_addc_u32 s9, s9, s13
	s_waitcnt vmcnt(7)
	v_lshlrev_b32_e32 v54, 16, v58
	v_and_b32_e32 v55, 0xffff0000, v58
	v_pk_mul_f32 v[96:97], v[54:55], v[54:55]
	v_lshlrev_b32_e32 v56, 16, v59
	v_and_b32_e32 v57, 0xffff0000, v59
	v_pk_mul_f32 v[98:99], v[56:57], v[56:57]
	v_add_f32_e32 v96, v96, v97
	v_lshlrev_b32_e32 v58, 16, v60
	v_and_b32_e32 v59, 0xffff0000, v60
	v_add_f32_e32 v96, v98, v96
	v_pk_mul_f32 v[100:101], v[58:59], v[58:59]
	v_add_f32_e32 v96, v99, v96
	v_lshlrev_b32_e32 v60, 16, v61
	v_and_b32_e32 v61, 0xffff0000, v61
	v_add_f32_e32 v96, v100, v96
	v_pk_mul_f32 v[102:103], v[60:61], v[60:61]
	v_add_f32_e32 v96, v101, v96
	s_waitcnt vmcnt(6)
	v_lshlrev_b32_e32 v104, 16, v68
	v_and_b32_e32 v105, 0xffff0000, v68
	v_lshlrev_b32_e32 v108, 16, v69
	v_and_b32_e32 v109, 0xffff0000, v69
	v_lshlrev_b32_e32 v112, 16, v70
	v_and_b32_e32 v113, 0xffff0000, v70
	v_lshlrev_b32_e32 v116, 16, v71
	v_and_b32_e32 v117, 0xffff0000, v71
	global_load_dwordx4 v[68:71], v[44:45], off offset:16
	global_load_dwordx4 v[88:91], v[44:45], off
	v_add_f32_e32 v96, v102, v96
	v_pk_mul_f32 v[106:107], v[104:105], v[104:105]
	v_add_f32_e32 v96, v103, v96
	v_add_f32_e32 v96, v106, v96
	v_pk_mul_f32 v[110:111], v[108:109], v[108:109]
	s_waitcnt vmcnt(7)
	v_lshlrev_b32_e32 v120, 16, v72
	v_and_b32_e32 v121, 0xffff0000, v72
	v_lshlrev_b32_e32 v124, 16, v73
	v_and_b32_e32 v125, 0xffff0000, v73
	v_lshlrev_b32_e32 v130, 16, v74
	v_and_b32_e32 v131, 0xffff0000, v74
	v_lshlrev_b32_e32 v134, 16, v75
	v_and_b32_e32 v135, 0xffff0000, v75
	global_load_dwordx4 v[72:75], v[46:47], off offset:16
	global_load_dwordx4 v[92:95], v[46:47], off
	v_add_f32_e32 v96, v107, v96
	v_add_f32_e32 v96, v110, v96
	v_pk_mul_f32 v[114:115], v[112:113], v[112:113]
	v_add_f32_e32 v96, v111, v96
	v_add_f32_e32 v96, v114, v96
	v_pk_mul_f32 v[118:119], v[116:117], v[116:117]
	v_add_f32_e32 v96, v115, v96
	v_add_f32_e32 v96, v118, v96
	v_pk_mul_f32 v[122:123], v[120:121], v[120:121]
	v_add_f32_e32 v96, v119, v96
	v_add_f32_e32 v96, v122, v96
	v_pk_mul_f32 v[126:127], v[124:125], v[124:125]
	v_add_f32_e32 v96, v123, v96
	v_add_f32_e32 v96, v126, v96
	v_pk_mul_f32 v[132:133], v[130:131], v[130:131]
	v_add_f32_e32 v96, v127, v96
	v_add_f32_e32 v96, v132, v96
	v_pk_mul_f32 v[136:137], v[134:135], v[134:135]
	v_add_f32_e32 v96, v133, v96
	s_waitcnt vmcnt(8)
; template <bool HAS_M, bool WRITE_X, bool WRITE_HN>
; __device__ __forceinline__ void seam_rows(const float* xin, const bf16_t* mb, const float* gpost, const float* gpre, float* xout, bf16_t* hn, int gw, int NGW, int lane) {
;     ...
;         if (HAS_M) {
;             float mv[32]; float ss = 0.f;
; #pragma unroll
;             for (int s = 0; s < 4; ++s) unpack8(*(const u32x4*)(mb + ro + s * 512), mv + s * 8);
; #pragma unroll
;             for (int i = 0; i < 32; ++i) ss += mv[i] * mv[i];
;             const float r1 = rsqrtf(wave_sum(ss) * (1.f / 2048.f) + 1e-6f);
; #pragma unroll
;             for (int s = 0; s < 4; ++s) { float g[8]; ld8f(gpost + s * 512 + lane * 8, g);
; #pragma unroll
;                 for (int i = 0; i < 8; ++i) v[s * 8 + i] += mv[s * 8 + i] * r1 * g[i]; }
;         }
;         if (WRITE_X) {
; #pragma unroll
;             for (int s = 0; s < 4; ++s) { *(f32x4*)(xout + ro + s * 512) = (f32x4){v[s * 8], v[s * 8 + 1], v[s * 8 + 2], v[s * 8 + 3]}; *(f32x4*)(xout + ro + s * 512 + 4) = (f32x4){v[s * 8 + 4], v[s * 8 + 5], v[s * 8 + 6], v[s * 8 + 7]}; }
;         }
;         if (WRITE_HN) {
;             float ss = 0.f;
; #pragma unroll
;             for (int i = 0; i < 32; ++i) ss += v[i] * v[i];
;             const float r2 = rsqrtf(wave_sum(ss) * (1.f / 2048.f) + 1e-6f);
	v_lshlrev_b32_e32 v138, 16, v76
	v_and_b32_e32 v139, 0xffff0000, v76
	v_add_f32_e32 v96, v136, v96
	v_pk_mul_f32 v[140:141], v[138:139], v[138:139]
	v_add_f32_e32 v96, v137, v96
	v_lshlrev_b32_e32 v76, 16, v77
	v_and_b32_e32 v77, 0xffff0000, v77
	v_add_f32_e32 v96, v140, v96
	v_pk_mul_f32 v[142:143], v[76:77], v[76:77]
	v_add_f32_e32 v96, v141, v96
	v_lshlrev_b32_e32 v144, 16, v78
	v_and_b32_e32 v145, 0xffff0000, v78
	v_add_f32_e32 v96, v142, v96
	v_pk_mul_f32 v[146:147], v[144:145], v[144:145]
	v_add_f32_e32 v96, v143, v96
	v_lshlrev_b32_e32 v78, 16, v79
	v_and_b32_e32 v79, 0xffff0000, v79
	v_add_f32_e32 v96, v146, v96
	v_pk_mul_f32 v[148:149], v[78:79], v[78:79]
	v_add_f32_e32 v96, v147, v96
	v_add_f32_e32 v96, v148, v96
	v_add_f32_e32 v96, v149, v96
	ds_bpermute_b32 v97, v62, v96
	s_waitcnt lgkmcnt(0)
	v_add_f32_e32 v96, v96, v97
	ds_bpermute_b32 v97, v63, v96
	s_waitcnt lgkmcnt(0)
	v_add_f32_e32 v96, v96, v97
	ds_bpermute_b32 v97, v64, v96
	s_waitcnt lgkmcnt(0)
	v_add_f32_e32 v96, v96, v97
	ds_bpermute_b32 v97, v65, v96
	s_waitcnt lgkmcnt(0)
	v_add_f32_e32 v96, v96, v97
	ds_bpermute_b32 v97, v66, v96
	s_waitcnt lgkmcnt(0)
	v_add_f32_e32 v96, v96, v97
	ds_bpermute_b32 v97, v67, v96
	s_waitcnt lgkmcnt(0)
	v_add_f32_e32 v96, v96, v97
	v_fmamk_f32 v96, v96, 0x3a000000, v209
	v_cmp_gt_f32_e32 vcc, s15, v96
	v_mul_f32_e32 v97, 0x4b800000, v96
	s_nop 0
	v_cndmask_b32_e32 v96, v96, v97, vcc
	v_rsq_f32_e32 v96, v96
	s_nop 0
	v_mul_f32_e32 v97, 0x45800000, v96
	v_cndmask_b32_e32 v96, v96, v97, vcc
	v_pk_mul_f32 v[54:55], v[96:97], v[54:55] op_sel_hi:[0,1]
	s_waitcnt vmcnt(6)
	v_pk_fma_f32 v[28:29], v[28:29], v[54:55], v[24:25]
	v_pk_mul_f32 v[24:25], v[96:97], v[56:57] op_sel_hi:[0,1]
	v_pk_fma_f32 v[30:31], v[30:31], v[24:25], v[26:27]
	v_pk_mul_f32 v[24:25], v[96:97], v[58:59] op_sel_hi:[0,1]
	v_pk_fma_f32 v[24:25], v[36:37], v[24:25], v[20:21]
	v_pk_mul_f32 v[20:21], v[96:97], v[60:61] op_sel_hi:[0,1]
	v_pk_fma_f32 v[26:27], v[38:39], v[20:21], v[22:23]
	v_pk_mul_f32 v[20:21], v[96:97], v[104:105] op_sel_hi:[0,1]
	s_waitcnt vmcnt(4)
	v_pk_fma_f32 v[20:21], v[84:85], v[20:21], v[16:17]
	v_pk_mul_f32 v[16:17], v[96:97], v[108:109] op_sel_hi:[0,1]
	v_pk_fma_f32 v[22:23], v[86:87], v[16:17], v[18:19]
	v_pk_mul_f32 v[16:17], v[96:97], v[112:113] op_sel_hi:[0,1]
	v_pk_fma_f32 v[16:17], v[80:81], v[16:17], v[12:13]
	v_pk_mul_f32 v[12:13], v[96:97], v[116:117] op_sel_hi:[0,1]
	v_pk_fma_f32 v[18:19], v[82:83], v[12:13], v[14:15]
	v_pk_mul_f32 v[12:13], v[96:97], v[120:121] op_sel_hi:[0,1]
	s_waitcnt vmcnt(2)
	v_pk_fma_f32 v[12:13], v[88:89], v[12:13], v[32:33]
	v_pk_mul_f32 v[32:33], v[96:97], v[130:131] op_sel_hi:[0,1]
	v_pk_fma_f32 v[8:9], v[68:69], v[32:33], v[8:9]
	v_pk_mul_f32 v[32:33], v[96:97], v[134:135] op_sel_hi:[0,1]
	v_pk_fma_f32 v[10:11], v[70:71], v[32:33], v[10:11]
	v_pk_mul_f32 v[32:33], v[96:97], v[138:139] op_sel_hi:[0,1]
	s_waitcnt vmcnt(0)
	v_pk_fma_f32 v[4:5], v[92:93], v[32:33], v[4:5]
	v_pk_mul_f32 v[32:33], v[96:97], v[76:77] op_sel_hi:[0,1]
	v_pk_fma_f32 v[6:7], v[94:95], v[32:33], v[6:7]
	v_pk_mul_f32 v[32:33], v[96:97], v[144:145] op_sel_hi:[0,1]
	v_pk_fma_f32 v[0:1], v[72:73], v[32:33], v[0:1]
	v_pk_mul_f32 v[32:33], v[96:97], v[78:79] op_sel_hi:[0,1]
	v_pk_fma_f32 v[2:3], v[74:75], v[32:33], v[2:3]
	v_lshl_add_u64 v[32:33], s[30:31], 0, v[128:129]
	v_pk_mul_f32 v[14:15], v[96:97], v[124:125] op_sel_hi:[0,1]
	global_store_dwordx4 v[32:33], v[28:31], off
	global_store_dwordx4 v[32:33], v[24:27], off offset:16
	global_store_dwordx4 v[32:33], v[20:23], off offset:2048
	global_store_dwordx4 v[32:33], v[16:19], off offset:2064
	v_add_co_u32_e32 v32, vcc, s2, v32
	v_pk_fma_f32 v[14:15], v[90:91], v[14:15], v[34:35]
	s_nop 0
	v_addc_co_u32_e32 v33, vcc, 0, v33, vcc
	global_store_dwordx4 v[32:33], v[12:15], off
	global_store_dwordx4 v[32:33], v[8:11], off offset:16
	global_store_dwordx4 v[32:33], v[4:7], off offset:2048
	global_store_dwordx4 v[32:33], v[0:3], off offset:2064
	v_pk_mul_f32 v[32:33], v[28:29], v[28:29]
	v_pk_mul_f32 v[34:35], v[30:31], v[30:31]
	v_add_f32_e32 v32, v32, v33
	v_add_f32_e32 v32, v34, v32
	v_pk_mul_f32 v[36:37], v[24:25], v[24:25]
	v_add_f32_e32 v32, v35, v32
	v_add_f32_e32 v32, v36, v32
	v_pk_mul_f32 v[38:39], v[26:27], v[26:27]
	v_add_f32_e32 v32, v37, v32
	v_add_f32_e32 v32, v38, v32
	v_pk_mul_f32 v[54:55], v[20:21], v[20:21]
	v_add_f32_e32 v32, v39, v32
	v_add_f32_e32 v32, v54, v32
	v_pk_mul_f32 v[56:57], v[22:23], v[22:23]
	v_add_f32_e32 v32, v55, v32
	v_add_f32_e32 v32, v56, v32
	v_add_f32_e32 v32, v57, v32
	v_pk_mul_f32 v[58:59], v[16:17], v[16:17]
	v_pk_mul_f32 v[60:61], v[18:19], v[18:19]
	v_add_f32_e32 v32, v58, v32
	v_add_f32_e32 v32, v59, v32
	v_add_f32_e32 v32, v60, v32
	v_pk_mul_f32 v[68:69], v[12:13], v[12:13]
	v_add_f32_e32 v32, v61, v32
	v_add_f32_e32 v32, v68, v32
	v_pk_mul_f32 v[70:71], v[14:15], v[14:15]
	v_add_f32_e32 v32, v69, v32
	v_add_f32_e32 v32, v70, v32
	v_pk_mul_f32 v[72:73], v[8:9], v[8:9]
	v_add_f32_e32 v32, v71, v32
	v_add_f32_e32 v32, v72, v32
	v_pk_mul_f32 v[74:75], v[10:11], v[10:11]
	v_add_f32_e32 v32, v73, v32
	v_add_f32_e32 v32, v74, v32
	v_pk_mul_f32 v[76:77], v[4:5], v[4:5]
	v_add_f32_e32 v32, v75, v32
	v_add_f32_e32 v32, v76, v32
	v_pk_mul_f32 v[78:79], v[6:7], v[6:7]
	v_add_f32_e32 v32, v77, v32
	v_add_f32_e32 v32, v78, v32
	v_pk_mul_f32 v[80:81], v[0:1], v[0:1]
	v_add_f32_e32 v32, v79, v32
	v_add_f32_e32 v32, v80, v32
	v_pk_mul_f32 v[82:83], v[2:3], v[2:3]
	v_add_f32_e32 v32, v81, v32
	v_add_f32_e32 v32, v82, v32
	v_add_f32_e32 v32, v83, v32
	ds_bpermute_b32 v33, v62, v32
	s_brev_b32 s2, 63
	s_add_u32 s30, s30, s12
	s_addc_u32 s31, s31, s13
	s_cmpk_gt_i32 s7, 0x3fff
	s_waitcnt lgkmcnt(0)
; __device__ __forceinline__ u32x4 pack8(const float* f) { u32x4 w; w.x = pk2(f[0], f[1]); w.y = pk2(f[2], f[3]); w.z = pk2(f[4], f[5]); w.w = pk2(f[6], f[7]); return w; }
; template <bool HAS_M, bool WRITE_X, bool WRITE_HN>
; __device__ __forceinline__ void seam_rows(const float* xin, const bf16_t* mb, const float* gpost, const float* gpre, float* xout, bf16_t* hn, int gw, int NGW, int lane) {
;     ...
;         if (WRITE_HN) {
;             float ss = 0.f;
; #pragma unroll
;             for (int i = 0; i < 32; ++i) ss += v[i] * v[i];
;             const float r2 = rsqrtf(wave_sum(ss) * (1.f / 2048.f) + 1e-6f);
; #pragma unroll
;             for (int s = 0; s < 4; ++s) { float g[8], o[8]; ld8f(gpre + s * 512 + lane * 8, g);
; #pragma unroll
;                 for (int i = 0; i < 8; ++i) o[i] = v[s * 8 + i] * r2 * g[i];
;                 *(u32x4*)(hn + ro + s * 512) = pack8(o); }
	v_add_f32_e32 v32, v32, v33
	ds_bpermute_b32 v33, v63, v32
	s_waitcnt lgkmcnt(0)
	v_add_f32_e32 v32, v32, v33
	ds_bpermute_b32 v33, v64, v32
	s_waitcnt lgkmcnt(0)
	v_add_f32_e32 v32, v32, v33
	ds_bpermute_b32 v33, v65, v32
	s_waitcnt lgkmcnt(0)
	v_add_f32_e32 v32, v32, v33
	ds_bpermute_b32 v33, v66, v32
	s_waitcnt lgkmcnt(0)
	v_add_f32_e32 v32, v32, v33
	ds_bpermute_b32 v33, v67, v32
	s_waitcnt lgkmcnt(0)
	v_add_f32_e32 v32, v32, v33
	v_fmamk_f32 v32, v32, 0x3a000000, v209
	v_cmp_gt_f32_e32 vcc, s15, v32
	v_mul_f32_e32 v33, 0x4b800000, v32
	s_nop 0
	v_cndmask_b32_e32 v32, v32, v33, vcc
	v_rsq_f32_e32 v32, v32
	s_nop 0
	v_mul_f32_e32 v33, 0x45800000, v32
	v_cndmask_b32_e32 v32, v32, v33, vcc
	v_mul_f32_e32 v24, v24, v32
	s_nop 0
	v_mul_f32_e32 v33, v152, v24
	v_mul_f32_e32 v24, v25, v32
	v_mul_f32_e32 v28, v28, v32
	v_mul_f32_e32 v34, v153, v24
	v_mul_f32_e32 v24, v26, v32
	s_nop 0
	v_mul_f32_e32 v28, v156, v28
	v_mul_f32_e32 v29, v29, v32
	v_mul_f32_e32 v35, v154, v24
	v_mul_f32_e32 v24, v27, v32
	v_mul_f32_e32 v29, v157, v29
	v_mul_f32_e32 v27, v155, v24
	v_cvt_pk_bf16_f32 v24, v28, v29
	v_add_co_u32_e32 v28, vcc, s2, v52
	v_mul_f32_e32 v30, v30, v32
	v_mul_f32_e32 v31, v31, v32
	v_addc_co_u32_e32 v29, vcc, -1, v53, vcc
	v_mul_f32_e32 v30, v158, v30
	v_mul_f32_e32 v31, v159, v31
	v_cvt_pk_bf16_f32 v25, v30, v31
	v_cvt_pk_bf16_f32 v26, v33, v34
	v_cvt_pk_bf16_f32 v27, v35, v27
	global_store_dwordx4 v[28:29], v[24:27], off offset:-3072
	s_nop 0
	v_mul_f32_e32 v16, v16, v32
	v_mul_f32_e32 v20, v20, v32
	v_mul_f32_e32 v21, v21, v32
	v_mul_f32_e32 v22, v22, v32
	v_mul_f32_e32 v23, v23, v32
	v_mul_f32_e32 v8, v8, v32
	v_mul_f32_e32 v12, v12, v32
	v_mul_f32_e32 v13, v13, v32
	v_mul_f32_e32 v14, v14, v32
	v_mul_f32_e32 v15, v15, v32
	v_mul_f32_e32 v0, v0, v32
	v_mul_f32_e32 v4, v4, v32
	v_mul_f32_e32 v5, v5, v32
	v_mul_f32_e32 v6, v6, v32
	v_mul_f32_e32 v7, v7, v32
	v_lshl_add_u64 v[52:53], v[52:53], 0, s[18:19]
	s_nop 0
	v_mul_f32_e32 v24, v160, v16
	v_mul_f32_e32 v16, v17, v32
	v_mul_f32_e32 v25, v161, v16
	v_mul_f32_e32 v16, v18, v32
	v_mul_f32_e32 v26, v162, v16
	v_mul_f32_e32 v16, v19, v32
	v_mul_f32_e32 v19, v163, v16
	s_nop 0
	v_mul_f32_e32 v20, v164, v20
	v_mul_f32_e32 v21, v165, v21
	v_mul_f32_e32 v22, v166, v22
	v_mul_f32_e32 v23, v167, v23
	v_cvt_pk_bf16_f32 v16, v20, v21
	v_cvt_pk_bf16_f32 v17, v22, v23
	v_cvt_pk_bf16_f32 v18, v24, v25
	v_cvt_pk_bf16_f32 v19, v26, v19
	global_store_dwordx4 v[28:29], v[16:19], off offset:-2048
	s_nop 0
	s_nop 0
	v_mul_f32_e32 v16, v168, v8
	v_mul_f32_e32 v8, v9, v32
	v_mul_f32_e32 v17, v169, v8
	v_mul_f32_e32 v8, v10, v32
	v_mul_f32_e32 v18, v170, v8
	v_mul_f32_e32 v8, v11, v32
	v_mul_f32_e32 v11, v171, v8
	s_nop 0
	v_mul_f32_e32 v12, v172, v12
	v_mul_f32_e32 v13, v173, v13
	v_mul_f32_e32 v14, v174, v14
	v_mul_f32_e32 v15, v175, v15
	v_cvt_pk_bf16_f32 v8, v12, v13
	v_cvt_pk_bf16_f32 v9, v14, v15
	v_cvt_pk_bf16_f32 v10, v16, v17
	v_cvt_pk_bf16_f32 v11, v18, v11
	global_store_dwordx4 v[28:29], v[8:11], off offset:-1024
	s_nop 0
	s_nop 0
	v_mul_f32_e32 v8, v176, v0
	v_mul_f32_e32 v0, v1, v32
	v_mul_f32_e32 v9, v177, v0
	v_mul_f32_e32 v0, v2, v32
	v_mul_f32_e32 v10, v178, v0
	v_mul_f32_e32 v0, v3, v32
	v_mul_f32_e32 v3, v179, v0
	s_nop 0
	v_mul_f32_e32 v4, v180, v4
	v_mul_f32_e32 v5, v181, v5
	v_mul_f32_e32 v6, v182, v6
	v_mul_f32_e32 v7, v183, v7
	v_cvt_pk_bf16_f32 v0, v4, v5
	v_cvt_pk_bf16_f32 v1, v6, v7
	v_cvt_pk_bf16_f32 v2, v8, v9
	v_cvt_pk_bf16_f32 v3, v10, v3
	global_store_dwordx4 v[28:29], v[0:3], off
	s_cbranch_scc0 .LBB0_466
	s_mov_b32 s17, s6

; template <bool HAS_M, bool WRITE_X, bool WRITE_HN>
; __device__ __forceinline__ void seam_rows(const float* xin, const bf16_t* mb, const float* gpost, const float* gpre, float* xout, bf16_t* hn, int gw, int NGW, int lane) {
;     for (int row = gw; row < M; row += NGW) {
;         const size_t ro = (size_t)row * DM + lane * 8;
;         float v[32];
; #pragma unroll
;         for (int s = 0; s < 4; ++s) ld8f(xin + ro + s * 512, v + s * 8);
;         if (HAS_M) {
;             float mv[32]; float ss = 0.f;
; #pragma unroll
;             for (int s = 0; s < 4; ++s) unpack8(*(const u32x4*)(mb + ro + s * 512), mv + s * 8);
; #pragma unroll
;             for (int i = 0; i < 32; ++i) ss += mv[i] * mv[i];
;             const float r1 = rsqrtf(wave_sum(ss) * (1.f / 2048.f) + 1e-6f);
; #pragma unroll
;             for (int s = 0; s < 4; ++s) { float g[8]; ld8f(gpost + s * 512 + lane * 8, g);
; #pragma unroll
;                 for (int i = 0; i < 8; ++i) v[s * 8 + i] += mv[s * 8 + i] * r1 * g[i]; }
;         }
;         if (WRITE_X) {
; #pragma unroll
;             for (int s = 0; s < 4; ++s) { *(f32x4*)(xout + ro + s * 512) = (f32x4){v[s * 8], v[s * 8 + 1], v[s * 8 + 2], v[s * 8 + 3]}; *(f32x4*)(xout + ro + s * 512 + 4) = (f32x4){v[s * 8 + 4], v[s * 8 + 5], v[s * 8 + 6], v[s * 8 + 7]}; }
;         }
;         if (WRITE_HN) {
;             float ss = 0.f;
; #pragma unroll
;             for (int i = 0; i < 32; ++i) ss += v[i] * v[i];
;             const float r2 = rsqrtf(wave_sum(ss) * (1.f / 2048.f) + 1e-6f);
; #pragma unroll
;             for (int s = 0; s < 4; ++s) { float g[8], o[8]; ld8f(gpre + s * 512 + lane * 8, g);
.LBB0_786:
	s_or_b64 exec, exec, s[6:7]
	s_mov_b64 s[26:27], 0x1000
	s_cmpk_gt_i32 s10, 0x3fff
	s_cbranch_scc1 .LBB0_789
	v_cmp_lt_i32_e32 vcc, v213, v212
	s_load_dwordx4 s[28:31], s[64:65], 0x0
	s_ashr_i32 s0, s24, 31
	v_cndmask_b32_e32 v0, v211, v213, vcc
	v_cmp_lt_i32_e32 vcc, v210, v212
	s_waitcnt vmcnt(17)
	v_lshlrev_b32_e32 v18, 2, v0
	s_ashr_i32 s1, s17, 31
	v_cndmask_b32_e32 v0, v211, v210, vcc
	s_waitcnt vmcnt(16)
	v_lshlrev_b32_e32 v19, 2, v0
	v_xor_b32_e32 v0, 4, v211
	v_cmp_lt_i32_e32 vcc, v0, v212
	s_add_u32 s6, s24, s17
	s_addc_u32 s7, s0, s1
	v_cndmask_b32_e32 v0, v211, v0, vcc
	s_waitcnt vmcnt(15)
	v_lshlrev_b32_e32 v20, 2, v0
	v_xor_b32_e32 v0, 8, v211
	v_cmp_lt_i32_e32 vcc, v0, v212
	s_lshl_b64 s[0:1], s[6:7], 13
	s_waitcnt lgkmcnt(0)
	s_add_u32 s0, s28, s0
	v_cndmask_b32_e32 v0, v211, v0, vcc
	s_waitcnt vmcnt(14)
	v_lshlrev_b32_e32 v21, 2, v0
	v_xor_b32_e32 v0, 16, v211
	v_cmp_lt_i32_e32 vcc, v0, v212
	v_lshlrev_b32_e32 v128, 5, v35
	s_addc_u32 s1, s29, s1
	v_cndmask_b32_e32 v0, v211, v0, vcc
	v_cmp_lt_i32_e32 vcc, v218, v212
	s_waitcnt vmcnt(13)
	v_lshlrev_b32_e32 v22, 2, v0
	s_ashr_i32 s17, s16, 31
	v_cndmask_b32_e32 v0, v211, v218, vcc
	s_waitcnt vmcnt(12)
	v_lshlrev_b32_e32 v23, 2, v0
	v_lshl_add_u64 v[0:1], s[0:1], 0, v[128:129]
	s_lshl_b64 s[0:1], s[16:17], 13
	s_lshl_b64 s[6:7], s[6:7], 12
	s_add_u32 s4, s4, s6
	v_lshl_add_u64 v[8:9], s[30:31], 0, v[128:129]
	v_lshlrev_b32_e32 v128, 4, v35
	s_addc_u32 s5, s5, s7
	v_lshl_add_u64 v[14:15], v[0:1], 0, s[26:27]
	v_lshl_add_u64 v[0:1], s[4:5], 0, v[128:129]
	s_mov_b64 s[4:5], 0x6100800
	v_lshl_add_u64 v[10:11], v[8:9], 0, s[26:27]
	v_lshl_add_u64 v[12:13], v[8:9], 0, s[74:75]
	v_lshl_add_u64 v[16:17], v[0:1], 0, s[4:5]
	s_lshl_b64 s[4:5], s[16:17], 12
	global_load_dwordx4 v[152:155], v[8:9], off offset:2048
	global_load_dwordx4 v[156:159], v[8:9], off offset:2064
	global_load_dwordx4 v[160:163], v[10:11], off
	global_load_dwordx4 v[164:167], v[10:11], off offset:16
	global_load_dwordx4 v[168:171], v[12:13], off
	global_load_dwordx4 v[172:175], v[12:13], off offset:16
; __device__ __forceinline__ u32x4 pack8(const float* f) { u32x4 w; w.x = pk2(f[0], f[1]); w.y = pk2(f[2], f[3]); w.z = pk2(f[4], f[5]); w.w = pk2(f[6], f[7]); return w; }
; template <bool HAS_M, bool WRITE_X, bool WRITE_HN>
; __device__ __forceinline__ void seam_rows(const float* xin, const bf16_t* mb, const float* gpost, const float* gpre, float* xout, bf16_t* hn, int gw, int NGW, int lane) {
;     for (int row = gw; row < M; row += NGW) {
;         const size_t ro = (size_t)row * DM + lane * 8;
;         float v[32];
; #pragma unroll
;         for (int s = 0; s < 4; ++s) ld8f(xin + ro + s * 512, v + s * 8);
;         if (HAS_M) {
;             float mv[32]; float ss = 0.f;
; #pragma unroll
;             for (int s = 0; s < 4; ++s) unpack8(*(const u32x4*)(mb + ro + s * 512), mv + s * 8);
; #pragma unroll
;             for (int i = 0; i < 32; ++i) ss += mv[i] * mv[i];
;             const float r1 = rsqrtf(wave_sum(ss) * (1.f / 2048.f) + 1e-6f);
; #pragma unroll
;             for (int s = 0; s < 4; ++s) { float g[8]; ld8f(gpost + s * 512 + lane * 8, g);
; #pragma unroll
;                 for (int i = 0; i < 8; ++i) v[s * 8 + i] += mv[s * 8 + i] * r1 * g[i]; }
;         }
;         if (WRITE_X) {
; #pragma unroll
;             for (int s = 0; s < 4; ++s) { *(f32x4*)(xout + ro + s * 512) = (f32x4){v[s * 8], v[s * 8 + 1], v[s * 8 + 2], v[s * 8 + 3]}; *(f32x4*)(xout + ro + s * 512 + 4) = (f32x4){v[s * 8 + 4], v[s * 8 + 5], v[s * 8 + 6], v[s * 8 + 7]}; }
;         }
;         if (WRITE_HN) {
;             float ss = 0.f;
; #pragma unroll
;             for (int i = 0; i < 32; ++i) ss += v[i] * v[i];
;             const float r2 = rsqrtf(wave_sum(ss) * (1.f / 2048.f) + 1e-6f);
; #pragma unroll
;             for (int s = 0; s < 4; ++s) { float g[8], o[8]; ld8f(gpre + s * 512 + lane * 8, g);
; #pragma unroll
;                 for (int i = 0; i < 8; ++i) o[i] = v[s * 8 + i] * r2 * g[i];
;                 *(u32x4*)(hn + ro + s * 512) = pack8(o); }
.LBB0_788:
	global_load_dwordx4 v[24:27], v[14:15], off offset:-4096
	global_load_dwordx4 v[0:3], v[14:15], off offset:2064
	global_load_dwordx4 v[28:31], v[14:15], off offset:-4080
	global_load_dwordx4 v[32:35], v[14:15], off offset:-2048
	global_load_dwordx4 v[36:39], v[14:15], off offset:-2032
	global_load_dwordx4 v[40:43], v[14:15], off
	global_load_dwordx4 v[44:47], v[14:15], off offset:16
	global_load_dwordx4 v[4:7], v[14:15], off offset:2048
	global_load_dwordx4 v[48:51], v[8:9], off offset:16
	global_load_dwordx4 v[52:55], v[8:9], off
	s_add_i32 s10, s10, s16
	v_lshl_add_u64 v[14:15], v[14:15], 0, s[0:1]
	s_cmpk_gt_i32 s10, 0x3fff
	s_waitcnt vmcnt(9)
	v_mul_f32_e32 v60, v25, v25
	v_fmac_f32_e32 v60, v24, v24
	v_fmac_f32_e32 v60, v26, v26
	v_fmac_f32_e32 v60, v27, v27
	s_waitcnt vmcnt(7)
	v_fmac_f32_e32 v60, v28, v28
	v_fmac_f32_e32 v60, v29, v29
	v_fmac_f32_e32 v60, v30, v30
	v_fmac_f32_e32 v60, v31, v31
	s_waitcnt vmcnt(6)
	v_fmac_f32_e32 v60, v32, v32
	v_fmac_f32_e32 v60, v33, v33
	v_fmac_f32_e32 v60, v34, v34
	v_fmac_f32_e32 v60, v35, v35
	s_waitcnt vmcnt(5)
	v_fmac_f32_e32 v60, v36, v36
	v_fmac_f32_e32 v60, v37, v37
	v_fmac_f32_e32 v60, v38, v38
	v_fmac_f32_e32 v60, v39, v39
	s_waitcnt vmcnt(4)
	v_fmac_f32_e32 v60, v40, v40
	v_fmac_f32_e32 v60, v41, v41
	v_fmac_f32_e32 v60, v42, v42
	v_fmac_f32_e32 v60, v43, v43
	s_waitcnt vmcnt(3)
	v_fmac_f32_e32 v60, v44, v44
	v_fmac_f32_e32 v60, v45, v45
	v_fmac_f32_e32 v60, v46, v46
	v_fmac_f32_e32 v60, v47, v47
	s_waitcnt vmcnt(2)
	v_fmac_f32_e32 v60, v4, v4
	v_fmac_f32_e32 v60, v5, v5
	v_fmac_f32_e32 v60, v6, v6
	v_pk_mul_f32 v[58:59], v[0:1], v[0:1]
	v_fmac_f32_e32 v60, v7, v7
	v_add_f32_e32 v58, v58, v60
	v_pk_mul_f32 v[56:57], v[2:3], v[2:3]
	v_add_f32_e32 v58, v59, v58
	v_add_f32_e32 v56, v56, v58
	v_add_f32_e32 v56, v57, v56
	ds_bpermute_b32 v57, v18, v56
	s_waitcnt lgkmcnt(0)
	v_add_f32_e32 v56, v56, v57
	ds_bpermute_b32 v57, v19, v56
	s_waitcnt lgkmcnt(0)
	v_add_f32_e32 v56, v56, v57
	ds_bpermute_b32 v57, v20, v56
	s_waitcnt lgkmcnt(0)
	v_add_f32_e32 v56, v56, v57
	ds_bpermute_b32 v57, v21, v56
	s_waitcnt lgkmcnt(0)
	v_add_f32_e32 v56, v56, v57
	ds_bpermute_b32 v57, v22, v56
	s_waitcnt lgkmcnt(0)
	v_add_f32_e32 v56, v56, v57
	ds_bpermute_b32 v57, v23, v56
	s_waitcnt lgkmcnt(0)
	v_add_f32_e32 v56, v56, v57
	v_fmamk_f32 v56, v56, 0x3a000000, v209
	v_mul_f32_e32 v57, 0x4b800000, v56
	v_cmp_gt_f32_e32 vcc, s15, v56
	s_nop 1
	v_cndmask_b32_e32 v56, v56, v57, vcc
	v_rsq_f32_e32 v56, v56
	s_nop 0
	v_mul_f32_e32 v57, 0x45800000, v56
	v_cndmask_b32_e32 v56, v56, v57, vcc
	v_mul_f32_e32 v24, v24, v56
	v_mul_f32_e32 v25, v25, v56
	v_mul_f32_e32 v26, v26, v56
	v_mul_f32_e32 v27, v27, v56
	v_mul_f32_e32 v28, v28, v56
	v_mul_f32_e32 v29, v29, v56
	v_mul_f32_e32 v30, v30, v56
	v_mul_f32_e32 v31, v31, v56
	s_waitcnt vmcnt(0)
	v_mul_f32_e32 v24, v52, v24
	v_mul_f32_e32 v25, v53, v25
	v_mul_f32_e32 v26, v54, v26
	v_mul_f32_e32 v27, v55, v27
	v_mul_f32_e32 v28, v48, v28
	v_mul_f32_e32 v29, v49, v29
	v_mul_f32_e32 v30, v50, v30
	v_mul_f32_e32 v31, v51, v31
	v_cvt_pk_bf16_f32 v24, v24, v25
	v_cvt_pk_bf16_f32 v25, v26, v27
	v_cvt_pk_bf16_f32 v26, v28, v29
	v_cvt_pk_bf16_f32 v27, v30, v31
	global_store_dwordx4 v[16:17], v[24:27], off offset:-2048
	s_nop 0
	v_mul_f32_e32 v32, v32, v56
	v_mul_f32_e32 v33, v33, v56
	v_mul_f32_e32 v34, v34, v56
	v_mul_f32_e32 v35, v35, v56
	v_mul_f32_e32 v36, v36, v56
	v_mul_f32_e32 v37, v37, v56
	v_mul_f32_e32 v38, v38, v56
	v_mul_f32_e32 v39, v39, v56
	v_mul_f32_e32 v3, v3, v56
	v_mul_f32_e32 v4, v4, v56
	v_mul_f32_e32 v5, v5, v56
	v_mul_f32_e32 v6, v6, v56
	v_mul_f32_e32 v7, v7, v56
	v_mul_f32_e32 v0, v0, v56
	v_mul_f32_e32 v1, v1, v56
	v_mul_f32_e32 v2, v2, v56
	s_nop 0
	v_mul_f32_e32 v24, v152, v32
	v_mul_f32_e32 v25, v153, v33
	v_mul_f32_e32 v26, v154, v34
	v_mul_f32_e32 v27, v155, v35
	s_nop 0
	v_mul_f32_e32 v28, v156, v36
	v_mul_f32_e32 v29, v157, v37
	v_mul_f32_e32 v30, v158, v38
	v_mul_f32_e32 v31, v159, v39
	v_cvt_pk_bf16_f32 v24, v24, v25
	v_cvt_pk_bf16_f32 v25, v26, v27
	v_cvt_pk_bf16_f32 v26, v28, v29
	v_cvt_pk_bf16_f32 v27, v30, v31
	global_store_dwordx4 v[16:17], v[24:27], off offset:-1024
	s_nop 0
	v_mul_f32_e32 v32, v40, v56
	v_mul_f32_e32 v33, v41, v56
	v_mul_f32_e32 v34, v42, v56
	v_mul_f32_e32 v35, v43, v56
	v_mul_f32_e32 v36, v44, v56
	v_mul_f32_e32 v37, v45, v56
	v_mul_f32_e32 v38, v46, v56
	v_mul_f32_e32 v39, v47, v56
	s_nop 0
	v_mul_f32_e32 v24, v160, v32
	v_mul_f32_e32 v25, v161, v33
	v_mul_f32_e32 v26, v162, v34
	v_mul_f32_e32 v27, v163, v35
	s_nop 0
	v_mul_f32_e32 v28, v164, v36
	v_mul_f32_e32 v29, v165, v37
	v_mul_f32_e32 v30, v166, v38
	v_mul_f32_e32 v31, v167, v39
	v_cvt_pk_bf16_f32 v24, v24, v25
	v_cvt_pk_bf16_f32 v25, v26, v27
	v_cvt_pk_bf16_f32 v26, v28, v29
	v_cvt_pk_bf16_f32 v27, v30, v31
	global_store_dwordx4 v[16:17], v[24:27], off
	s_nop 0
	s_nop 0
	v_mul_f32_e32 v4, v168, v4
	s_nop 0
	v_mul_f32_e32 v3, v175, v3
	v_mul_f32_e32 v5, v169, v5
	v_mul_f32_e32 v6, v170, v6
	v_mul_f32_e32 v7, v171, v7
	v_mul_f32_e32 v24, v172, v0
	v_mul_f32_e32 v25, v173, v1
	v_mul_f32_e32 v26, v174, v2
	v_cvt_pk_bf16_f32 v0, v4, v5
	v_cvt_pk_bf16_f32 v1, v6, v7
	v_cvt_pk_bf16_f32 v2, v24, v25
	v_cvt_pk_bf16_f32 v3, v26, v3
	global_store_dwordx4 v[16:17], v[0:3], off offset:1024
	v_lshl_add_u64 v[16:17], v[16:17], 0, s[4:5]
	s_cbranch_scc0 .LBB0_788
